# EpiRes epilogues: f32 residual loads marked nt (streaming, read once)
# baseline (speedup 1.0000x reference)
; #define EPI_IT_ROW(it) EPI_ROW((it) >> 2, (it) & 3)
; #define EPI_PACK8(v0, v1) (u32x4){pk2((v0)[0], (v0)[1]), pk2((v0)[2], (v0)[3]), pk2((v1)[0], (v1)[1]), pk2((v1)[2], (v1)[3])}
;     __device__ __forceinline__ void operator()(AccRef acc, const Unit& u, int wr, int wc, int fr, int fq) const {
;     ...
;         for (int bj = 0; bj < 2; ++bj) { const size_t p = (size_t)EPI_IT_ROW(0) * DM + EPI_COL(bj); xc[bj][0] = *(const f32x4*)(xin + p); xc[bj][1] = *(const f32x4*)(xin + p + 4); }
; #pragma unroll
;         for (int it = 0; it < 8; ++it) { const int ai = it >> 2, m = it & 3, row = EPI_IT_ROW(it);
;             if (it + 1 < 8) {
; #pragma unroll
;                 for (int bj = 0; bj < 2; ++bj) { const size_t p = (size_t)EPI_IT_ROW(it + 1) * DM + EPI_COL(bj); xn[bj][0] = *(const f32x4*)(xin + p); xn[bj][1] = *(const f32x4*)(xin + p + 4); } }
;             float q = 0.f;
; #pragma unroll
;             for (int bj = 0; bj < 2; ++bj) { const size_t p = (size_t)row * DM + EPI_COL(bj);
;                 const f32x4 x0 = xc[bj][0] + acc[ai][bj][m][0], x1 = xc[bj][1] + acc[ai][bj][m][1];
;                 __builtin_nontemporal_store(x0, (f32x4*)(xout + p)); __builtin_nontemporal_store(x1, (f32x4*)(xout + p + 4));
;                 *(u32x4*)(xb + p) = EPI_PACK8(x0, x1);
;                 q += EPI_SQ8(x0, x1); }
;             q += __shfl_xor(q, 16); q += __shfl_xor(q, 32);
;             if (fq == 0) atomicAdd(ssout + row, q);
; #pragma unroll
;             for (int bj = 0; bj < 2; ++bj) { xc[bj][0] = xn[bj][0]; xc[bj][1] = xn[bj][1]; } }
.LBB0_460:
	s_lshl_b32 s1, s34, 8
	v_mov_b32_e32 v128, v171
	v_mov_b32_e32 v168, v170
	s_add_i32 s1, s1, s63
	s_lshl_b32 s0, s0, 8
	s_or_b32 s0, s0, s64
	v_add_u32_e32 v164, s1, v128
	v_ashrrev_i32_e32 v165, 31, v164
	v_lshl_add_u32 v162, v168, 3, s0
	v_lshlrev_b64 v[128:129], 12, v[164:165]
	v_ashrrev_i32_e32 v163, 31, v162
	v_lshl_add_u64 v[128:129], s[16:17], 0, v[128:129]
	v_lshlrev_b64 v[130:131], 2, v[162:163]
	v_add_u32_e32 v160, 0x80, v162
	v_lshl_add_u64 v[132:133], v[128:129], 0, v[130:131]
	v_ashrrev_i32_e32 v161, 31, v160
	global_load_dwordx4 v[180:183], v[132:133], off offset:16 nt
	global_load_dwordx4 v[184:187], v[132:133], off nt
	v_lshlrev_b64 v[132:133], 2, v[160:161]
	v_lshl_add_u64 v[128:129], v[128:129], 0, v[132:133]
	global_load_dwordx4 v[188:191], v[128:129], off nt
	global_load_dwordx4 v[192:195], v[128:129], off offset:16 nt
	v_add_u32_e32 v166, 16, v164
	v_ashrrev_i32_e32 v167, 31, v166
	v_lshlrev_b64 v[128:129], 12, v[166:167]
	v_lshl_add_u64 v[128:129], s[16:17], 0, v[128:129]
	v_lshl_add_u64 v[130:131], v[128:129], 0, v[130:131]
	v_lshl_add_u64 v[132:133], v[128:129], 0, v[132:133]
	global_load_dwordx4 v[136:139], v[130:131], off offset:16 nt
	global_load_dwordx4 v[140:143], v[130:131], off nt
	s_nop 0
	global_load_dwordx4 v[128:131], v[132:133], off offset:16 nt
	s_nop 0
	global_load_dwordx4 v[132:135], v[132:133], off nt
	v_and_b32_e32 v178, 64, v177
	v_xor_b32_e32 v169, 16, v177
	v_add_u32_e32 v178, 64, v178
	v_cmp_lt_i32_e64 s[0:1], v169, v178
	v_xor_b32_e32 v179, 32, v177
	v_cmp_eq_u32_e32 vcc, 0, v168
	v_cndmask_b32_e64 v168, v177, v169, s[0:1]
	v_cmp_lt_i32_e64 s[0:1], v179, v178
	v_lshlrev_b32_e32 v178, 2, v168
	v_lshlrev_b64 v[168:169], 10, v[164:165]
	v_lshl_add_u64 v[196:197], v[168:169], 0, v[162:163]
	v_lshl_add_u64 v[198:199], v[196:197], 2, s[48:49]
	v_cndmask_b32_e64 v179, v177, v179, s[0:1]
	v_lshl_add_u64 v[168:169], v[168:169], 0, v[160:161]
	v_lshl_add_u64 v[196:197], v[196:197], 1, s[24:25]
	v_lshl_add_u64 v[200:201], v[168:169], 2, s[48:49]
	v_lshlrev_b32_e32 v179, 2, v179
	s_waitcnt vmcnt(0)
	v_pk_add_f32 v[122:123], v[122:123], v[182:183]
	v_pk_add_f32 v[126:127], v[126:127], v[186:187]
	v_pk_add_f32 v[124:125], v[124:125], v[184:185]
	v_pk_add_f32 v[118:119], v[118:119], v[190:191]
	v_pk_add_f32 v[116:117], v[116:117], v[188:189]
	v_pk_add_f32 v[120:121], v[120:121], v[180:181]
	v_pk_add_f32 v[180:181], v[112:113], v[192:193]
	global_store_dwordx4 v[198:199], v[124:127], off nt
	global_store_dwordx4 v[198:199], v[120:123], off offset:16 nt
	v_cvt_pk_bf16_f32 v112, v124, v125
	v_cvt_pk_bf16_f32 v113, v126, v127
	v_mul_f32_e32 v185, v117, v117
	v_mul_f32_e32 v125, v125, v125
	v_mul_f32_e32 v127, v127, v127
	v_mul_f32_e32 v186, v119, v119
	v_pk_add_f32 v[182:183], v[114:115], v[194:195]
	v_cvt_pk_bf16_f32 v114, v120, v121
	v_cvt_pk_bf16_f32 v115, v122, v123
	v_mul_f32_e32 v121, v121, v121
	v_mul_f32_e32 v123, v123, v123
	v_mul_f32_e32 v187, v181, v181
	v_fmac_f32_e32 v125, v124, v124
	v_fmac_f32_e32 v127, v126, v126
	v_fmac_f32_e32 v185, v116, v116
	v_fmac_f32_e32 v186, v118, v118
	v_mul_f32_e32 v188, v183, v183
	v_fmac_f32_e32 v121, v120, v120
	v_fmac_f32_e32 v123, v122, v122
	v_fmac_f32_e32 v187, v180, v180
	v_add_f32_e32 v120, v125, v127
	v_add_f32_e32 v122, v185, v186
	v_fmac_f32_e32 v188, v182, v182
	v_add_f32_e32 v120, v120, v121
	v_add_f32_e32 v121, v122, v187
	v_add_f32_e32 v120, v123, v120
	v_add_f32_e32 v121, v188, v121
	v_add_f32_e32 v120, v120, v121
	ds_bpermute_b32 v121, v178, v120
	global_store_dwordx4 v[196:197], v[112:115], off
	global_store_dwordx4 v[200:201], v[116:119], off nt
	global_store_dwordx4 v[200:201], v[180:183], off offset:16 nt
	v_lshl_add_u64 v[114:115], v[168:169], 1, s[24:25]
	v_cvt_pk_bf16_f32 v184, v116, v117
	v_cvt_pk_bf16_f32 v185, v118, v119
	s_waitcnt lgkmcnt(0)
	v_add_f32_e32 v112, v120, v121
	ds_bpermute_b32 v113, v179, v112
	v_cvt_pk_bf16_f32 v186, v180, v181
	v_cvt_pk_bf16_f32 v187, v182, v183
	global_store_dwordx4 v[114:115], v[184:187], off
	s_and_saveexec_b64 s[0:1], vcc
	s_cbranch_execz .LBB0_462
	v_lshl_add_u64 v[114:115], v[164:165], 2, s[10:11]
	s_waitcnt lgkmcnt(0)
	v_add_f32_e32 v112, v112, v113
	global_atomic_add_f32 v[114:115], v112, off
.LBB0_462:
	s_or_b64 exec, exec, s[0:1]
	v_add_u32_e32 v168, 32, v164
	v_ashrrev_i32_e32 v169, 31, v168
	s_waitcnt lgkmcnt(0)
	v_lshlrev_b64 v[112:113], 12, v[168:169]
	v_lshl_add_u64 v[112:113], s[16:17], 0, v[112:113]
	v_lshl_add_u64 v[114:115], v[162:163], 2, v[112:113]
	v_lshl_add_u64 v[116:117], v[160:161], 2, v[112:113]
	global_load_dwordx4 v[120:123], v[114:115], off offset:16 nt
	global_load_dwordx4 v[124:127], v[114:115], off nt
	s_nop 0
	global_load_dwordx4 v[112:115], v[116:117], off offset:16 nt
	s_nop 0
	global_load_dwordx4 v[116:119], v[116:117], off nt
	v_lshlrev_b64 v[180:181], 10, v[166:167]
	v_lshl_add_u64 v[182:183], v[180:181], 0, v[162:163]
	v_pk_add_f32 v[110:111], v[110:111], v[142:143]
	v_pk_add_f32 v[108:109], v[108:109], v[140:141]
	v_pk_add_f32 v[104:105], v[104:105], v[136:137]
	v_lshl_add_u64 v[136:137], v[182:183], 2, s[48:49]
	v_pk_add_f32 v[106:107], v[106:107], v[138:139]
	global_store_dwordx4 v[136:137], v[108:111], off nt
	global_store_dwordx4 v[136:137], v[104:107], off offset:16 nt
	v_cvt_pk_bf16_f32 v136, v108, v109
	v_cvt_pk_bf16_f32 v138, v104, v105
	v_pk_add_f32 v[102:103], v[102:103], v[134:135]
	v_mul_f32_e32 v109, v109, v109
	v_fmac_f32_e32 v109, v108, v108
	v_mul_f32_e32 v108, v111, v111
	v_fmac_f32_e32 v108, v110, v110
	v_mul_f32_e32 v105, v105, v105
	v_add_f32_e32 v108, v109, v108
	v_fmac_f32_e32 v105, v104, v104
	v_add_f32_e32 v104, v108, v105
	v_mul_f32_e32 v105, v107, v107
	v_pk_add_f32 v[100:101], v[100:101], v[132:133]
	v_cvt_pk_bf16_f32 v139, v106, v107
	v_fmac_f32_e32 v105, v106, v106
	v_pk_add_f32 v[106:107], v[98:99], v[130:131]
	v_mul_f32_e32 v98, v101, v101
	v_mul_f32_e32 v99, v103, v103
	v_cvt_pk_bf16_f32 v137, v110, v111
	v_add_f32_e32 v110, v105, v104
	v_pk_add_f32 v[104:105], v[96:97], v[128:129]
	v_fmac_f32_e32 v98, v100, v100
	v_fmac_f32_e32 v99, v102, v102
	v_add_f32_e32 v98, v98, v99
	v_mul_f32_e32 v99, v105, v105
	v_fmac_f32_e32 v99, v104, v104
	v_add_f32_e32 v98, v98, v99
	v_mul_f32_e32 v99, v107, v107
	v_fmac_f32_e32 v99, v106, v106
	v_add_f32_e32 v98, v99, v98
	v_add_f32_e32 v110, v110, v98
	ds_bpermute_b32 v111, v178, v110
	v_lshl_add_u64 v[108:109], v[180:181], 0, v[160:161]
	v_lshl_add_u64 v[140:141], v[182:183], 1, s[24:25]
	v_lshl_add_u64 v[96:97], v[108:109], 2, s[48:49]
	global_store_dwordx4 v[140:141], v[136:139], off
	global_store_dwordx4 v[96:97], v[100:103], off nt
	global_store_dwordx4 v[96:97], v[104:107], off offset:16 nt
	s_waitcnt lgkmcnt(0)
; #define EPI_IT_ROW(it) EPI_ROW((it) >> 2, (it) & 3)
; #define EPI_PACK8(v0, v1) (u32x4){pk2((v0)[0], (v0)[1]), pk2((v0)[2], (v0)[3]), pk2((v1)[0], (v1)[1]), pk2((v1)[2], (v1)[3])}
;     __device__ __forceinline__ void operator()(AccRef acc, const Unit& u, int wr, int wc, int fr, int fq) const {
;     ...
;         for (int it = 0; it < 8; ++it) { const int ai = it >> 2, m = it & 3, row = EPI_IT_ROW(it);
;             if (it + 1 < 8) {
; #pragma unroll
;                 for (int bj = 0; bj < 2; ++bj) { const size_t p = (size_t)EPI_IT_ROW(it + 1) * DM + EPI_COL(bj); xn[bj][0] = *(const f32x4*)(xin + p); xn[bj][1] = *(const f32x4*)(xin + p + 4); } }
;             float q = 0.f;
; #pragma unroll
;             for (int bj = 0; bj < 2; ++bj) { const size_t p = (size_t)row * DM + EPI_COL(bj);
;                 const f32x4 x0 = xc[bj][0] + acc[ai][bj][m][0], x1 = xc[bj][1] + acc[ai][bj][m][1];
;                 __builtin_nontemporal_store(x0, (f32x4*)(xout + p)); __builtin_nontemporal_store(x1, (f32x4*)(xout + p + 4));
;                 *(u32x4*)(xb + p) = EPI_PACK8(x0, x1);
;                 q += EPI_SQ8(x0, x1); }
;             q += __shfl_xor(q, 16); q += __shfl_xor(q, 32);
;             if (fq == 0) atomicAdd(ssout + row, q);
; #pragma unroll
;             for (int bj = 0; bj < 2; ++bj) { xc[bj][0] = xn[bj][0]; xc[bj][1] = xn[bj][1]; } }
	v_add_f32_e32 v96, v110, v111
	ds_bpermute_b32 v97, v179, v96
	v_cvt_pk_bf16_f32 v99, v102, v103
	v_lshl_add_u64 v[102:103], v[108:109], 1, s[24:25]
	v_cvt_pk_bf16_f32 v98, v100, v101
	v_cvt_pk_bf16_f32 v100, v104, v105
	v_cvt_pk_bf16_f32 v101, v106, v107
	global_store_dwordx4 v[102:103], v[98:101], off
	s_and_saveexec_b64 s[0:1], vcc
	s_cbranch_execz .LBB0_464
	v_lshl_add_u64 v[98:99], v[166:167], 2, s[10:11]
	s_waitcnt lgkmcnt(0)
	v_add_f32_e32 v96, v96, v97
	global_atomic_add_f32 v[98:99], v96, off
.LBB0_464:
	s_or_b64 exec, exec, s[0:1]
	v_add_u32_e32 v128, 48, v164
	v_ashrrev_i32_e32 v129, 31, v128
	s_waitcnt lgkmcnt(0)
	v_lshlrev_b64 v[96:97], 12, v[128:129]
	v_lshl_add_u64 v[96:97], s[16:17], 0, v[96:97]
	v_lshl_add_u64 v[98:99], v[162:163], 2, v[96:97]
	v_lshl_add_u64 v[100:101], v[160:161], 2, v[96:97]
	global_load_dwordx4 v[104:107], v[98:99], off offset:16 nt
	global_load_dwordx4 v[108:111], v[98:99], off nt
	s_nop 0
	global_load_dwordx4 v[96:99], v[100:101], off offset:16 nt
	s_nop 0
	global_load_dwordx4 v[100:103], v[100:101], off nt
	v_lshlrev_b64 v[130:131], 10, v[168:169]
	v_lshl_add_u64 v[132:133], v[130:131], 0, v[162:163]
	s_waitcnt vmcnt(12)
	v_pk_add_f32 v[94:95], v[94:95], v[126:127]
	v_pk_add_f32 v[92:93], v[92:93], v[124:125]
	v_pk_add_f32 v[88:89], v[88:89], v[120:121]
	v_lshl_add_u64 v[120:121], v[132:133], 2, s[48:49]
	v_pk_add_f32 v[90:91], v[90:91], v[122:123]
	global_store_dwordx4 v[120:121], v[92:95], off nt
	global_store_dwordx4 v[120:121], v[88:91], off offset:16 nt
	v_cvt_pk_bf16_f32 v120, v92, v93
	v_cvt_pk_bf16_f32 v122, v88, v89
	s_waitcnt vmcnt(12)
	v_pk_add_f32 v[86:87], v[86:87], v[118:119]
	v_mul_f32_e32 v93, v93, v93
	v_fmac_f32_e32 v93, v92, v92
	v_mul_f32_e32 v92, v95, v95
	v_fmac_f32_e32 v92, v94, v94
	v_mul_f32_e32 v89, v89, v89
	v_add_f32_e32 v92, v93, v92
	v_fmac_f32_e32 v89, v88, v88
	v_add_f32_e32 v88, v92, v89
	v_mul_f32_e32 v89, v91, v91
	v_pk_add_f32 v[84:85], v[84:85], v[116:117]
	v_cvt_pk_bf16_f32 v123, v90, v91
	v_fmac_f32_e32 v89, v90, v90
	v_pk_add_f32 v[90:91], v[82:83], v[114:115]
	v_mul_f32_e32 v82, v85, v85
	v_mul_f32_e32 v83, v87, v87
	v_cvt_pk_bf16_f32 v121, v94, v95
	v_add_f32_e32 v94, v89, v88
	v_pk_add_f32 v[88:89], v[80:81], v[112:113]
	v_fmac_f32_e32 v82, v84, v84
	v_fmac_f32_e32 v83, v86, v86
	v_add_f32_e32 v82, v82, v83
	v_mul_f32_e32 v83, v89, v89
	v_fmac_f32_e32 v83, v88, v88
	v_add_f32_e32 v82, v82, v83
	v_mul_f32_e32 v83, v91, v91
	v_fmac_f32_e32 v83, v90, v90
	v_add_f32_e32 v82, v83, v82
	v_add_f32_e32 v94, v94, v82
	ds_bpermute_b32 v95, v178, v94
	v_lshl_add_u64 v[92:93], v[130:131], 0, v[160:161]
	v_lshl_add_u64 v[124:125], v[132:133], 1, s[24:25]
	v_lshl_add_u64 v[80:81], v[92:93], 2, s[48:49]
	global_store_dwordx4 v[124:125], v[120:123], off
	global_store_dwordx4 v[80:81], v[84:87], off nt
	global_store_dwordx4 v[80:81], v[88:91], off offset:16 nt
	s_waitcnt lgkmcnt(0)
	v_add_f32_e32 v80, v94, v95
	ds_bpermute_b32 v81, v179, v80
	v_cvt_pk_bf16_f32 v83, v86, v87
	v_lshl_add_u64 v[86:87], v[92:93], 1, s[24:25]
	v_cvt_pk_bf16_f32 v82, v84, v85
	v_cvt_pk_bf16_f32 v84, v88, v89
	v_cvt_pk_bf16_f32 v85, v90, v91
	global_store_dwordx4 v[86:87], v[82:85], off
	s_and_saveexec_b64 s[0:1], vcc
	s_cbranch_execz .LBB0_466
	v_lshl_add_u64 v[82:83], v[168:169], 2, s[10:11]
	s_waitcnt lgkmcnt(0)
	v_add_f32_e32 v80, v80, v81
	global_atomic_add_f32 v[82:83], v80, off
.LBB0_466:
	s_or_b64 exec, exec, s[0:1]
	v_add_u32_e32 v112, 0x80, v164
	v_ashrrev_i32_e32 v113, 31, v112
	s_waitcnt lgkmcnt(0)
	v_lshlrev_b64 v[80:81], 12, v[112:113]
	v_lshl_add_u64 v[80:81], s[16:17], 0, v[80:81]
	v_lshl_add_u64 v[82:83], v[162:163], 2, v[80:81]
	v_lshl_add_u64 v[84:85], v[160:161], 2, v[80:81]
	global_load_dwordx4 v[88:91], v[82:83], off offset:16 nt
	global_load_dwordx4 v[92:95], v[82:83], off nt
	s_nop 0
	global_load_dwordx4 v[80:83], v[84:85], off offset:16 nt
	s_nop 0
	global_load_dwordx4 v[84:87], v[84:85], off nt
	v_lshlrev_b64 v[114:115], 10, v[128:129]
	v_lshl_add_u64 v[116:117], v[114:115], 0, v[162:163]
	s_waitcnt vmcnt(12)
	v_pk_add_f32 v[78:79], v[78:79], v[110:111]
	v_pk_add_f32 v[76:77], v[76:77], v[108:109]
	v_pk_add_f32 v[72:73], v[72:73], v[104:105]
	v_lshl_add_u64 v[104:105], v[116:117], 2, s[48:49]
	v_pk_add_f32 v[74:75], v[74:75], v[106:107]
	global_store_dwordx4 v[104:105], v[76:79], off nt
	global_store_dwordx4 v[104:105], v[72:75], off offset:16 nt
	v_cvt_pk_bf16_f32 v104, v76, v77
	v_cvt_pk_bf16_f32 v106, v72, v73
	s_waitcnt vmcnt(12)
	v_pk_add_f32 v[70:71], v[70:71], v[102:103]
	v_mul_f32_e32 v77, v77, v77
	v_fmac_f32_e32 v77, v76, v76
	v_mul_f32_e32 v76, v79, v79
	v_fmac_f32_e32 v76, v78, v78
	v_mul_f32_e32 v73, v73, v73
	v_add_f32_e32 v76, v77, v76
	v_fmac_f32_e32 v73, v72, v72
	v_add_f32_e32 v72, v76, v73
	v_mul_f32_e32 v73, v75, v75
	v_pk_add_f32 v[68:69], v[68:69], v[100:101]
	v_cvt_pk_bf16_f32 v107, v74, v75
	v_fmac_f32_e32 v73, v74, v74
	v_pk_add_f32 v[74:75], v[66:67], v[98:99]
	v_mul_f32_e32 v66, v69, v69
	v_mul_f32_e32 v67, v71, v71
	v_cvt_pk_bf16_f32 v105, v78, v79
	v_add_f32_e32 v78, v73, v72
	v_pk_add_f32 v[72:73], v[64:65], v[96:97]
	v_fmac_f32_e32 v66, v68, v68
	v_fmac_f32_e32 v67, v70, v70
	v_add_f32_e32 v66, v66, v67
	v_mul_f32_e32 v67, v73, v73
	v_fmac_f32_e32 v67, v72, v72
	v_add_f32_e32 v66, v66, v67
	v_mul_f32_e32 v67, v75, v75
	v_fmac_f32_e32 v67, v74, v74
	v_add_f32_e32 v66, v67, v66
	v_add_f32_e32 v78, v78, v66
	ds_bpermute_b32 v79, v178, v78
	v_lshl_add_u64 v[76:77], v[114:115], 0, v[160:161]
	v_lshl_add_u64 v[108:109], v[116:117], 1, s[24:25]
	v_lshl_add_u64 v[64:65], v[76:77], 2, s[48:49]
	global_store_dwordx4 v[108:109], v[104:107], off
	global_store_dwordx4 v[64:65], v[68:71], off nt
	global_store_dwordx4 v[64:65], v[72:75], off offset:16 nt
	s_waitcnt lgkmcnt(0)
	v_add_f32_e32 v64, v78, v79
	ds_bpermute_b32 v65, v179, v64
	v_cvt_pk_bf16_f32 v67, v70, v71
	v_lshl_add_u64 v[70:71], v[76:77], 1, s[24:25]
	v_cvt_pk_bf16_f32 v66, v68, v69
	v_cvt_pk_bf16_f32 v68, v72, v73
	v_cvt_pk_bf16_f32 v69, v74, v75
	global_store_dwordx4 v[70:71], v[66:69], off
	s_and_saveexec_b64 s[0:1], vcc
	s_cbranch_execz .LBB0_468
	v_lshl_add_u64 v[66:67], v[128:129], 2, s[10:11]
	s_waitcnt lgkmcnt(0)
	v_add_f32_e32 v64, v64, v65
	global_atomic_add_f32 v[66:67], v64, off
; #define EPI_IT_ROW(it) EPI_ROW((it) >> 2, (it) & 3)
; #define EPI_PACK8(v0, v1) (u32x4){pk2((v0)[0], (v0)[1]), pk2((v0)[2], (v0)[3]), pk2((v1)[0], (v1)[1]), pk2((v1)[2], (v1)[3])}
;     __device__ __forceinline__ void operator()(AccRef acc, const Unit& u, int wr, int wc, int fr, int fq) const {
;     ...
;         for (int it = 0; it < 8; ++it) { const int ai = it >> 2, m = it & 3, row = EPI_IT_ROW(it);
;             if (it + 1 < 8) {
; #pragma unroll
;                 for (int bj = 0; bj < 2; ++bj) { const size_t p = (size_t)EPI_IT_ROW(it + 1) * DM + EPI_COL(bj); xn[bj][0] = *(const f32x4*)(xin + p); xn[bj][1] = *(const f32x4*)(xin + p + 4); } }
;             float q = 0.f;
; #pragma unroll
;             for (int bj = 0; bj < 2; ++bj) { const size_t p = (size_t)row * DM + EPI_COL(bj);
;                 const f32x4 x0 = xc[bj][0] + acc[ai][bj][m][0], x1 = xc[bj][1] + acc[ai][bj][m][1];
;                 __builtin_nontemporal_store(x0, (f32x4*)(xout + p)); __builtin_nontemporal_store(x1, (f32x4*)(xout + p + 4));
;                 *(u32x4*)(xb + p) = EPI_PACK8(x0, x1);
;                 q += EPI_SQ8(x0, x1); }
;             q += __shfl_xor(q, 16); q += __shfl_xor(q, 32);
;             if (fq == 0) atomicAdd(ssout + row, q);
; #pragma unroll
;             for (int bj = 0; bj < 2; ++bj) { xc[bj][0] = xn[bj][0]; xc[bj][1] = xn[bj][1]; } }
.LBB0_468:
	s_or_b64 exec, exec, s[0:1]
	v_add_u32_e32 v96, 0x90, v164
	v_ashrrev_i32_e32 v97, 31, v96
	s_waitcnt lgkmcnt(0)
	v_lshlrev_b64 v[64:65], 12, v[96:97]
	v_lshl_add_u64 v[64:65], s[16:17], 0, v[64:65]
	v_lshl_add_u64 v[66:67], v[162:163], 2, v[64:65]
	v_lshl_add_u64 v[68:69], v[160:161], 2, v[64:65]
	global_load_dwordx4 v[72:75], v[66:67], off offset:16 nt
	global_load_dwordx4 v[76:79], v[66:67], off nt
	s_nop 0
	global_load_dwordx4 v[64:67], v[68:69], off offset:16 nt
	s_nop 0
	global_load_dwordx4 v[68:71], v[68:69], off nt
	v_lshlrev_b64 v[98:99], 10, v[112:113]
	v_lshl_add_u64 v[100:101], v[98:99], 0, v[162:163]
	s_waitcnt vmcnt(12)
	v_pk_add_f32 v[62:63], v[62:63], v[94:95]
	v_pk_add_f32 v[60:61], v[60:61], v[92:93]
	v_pk_add_f32 v[56:57], v[56:57], v[88:89]
	v_lshl_add_u64 v[88:89], v[100:101], 2, s[48:49]
	v_pk_add_f32 v[58:59], v[58:59], v[90:91]
	global_store_dwordx4 v[88:89], v[60:63], off nt
	global_store_dwordx4 v[88:89], v[56:59], off offset:16 nt
	v_cvt_pk_bf16_f32 v88, v60, v61
	v_cvt_pk_bf16_f32 v90, v56, v57
	s_waitcnt vmcnt(12)
	v_pk_add_f32 v[54:55], v[54:55], v[86:87]
	v_mul_f32_e32 v61, v61, v61
	v_fmac_f32_e32 v61, v60, v60
	v_mul_f32_e32 v60, v63, v63
	v_fmac_f32_e32 v60, v62, v62
	v_mul_f32_e32 v57, v57, v57
	v_add_f32_e32 v60, v61, v60
	v_fmac_f32_e32 v57, v56, v56
	v_add_f32_e32 v56, v60, v57
	v_mul_f32_e32 v57, v59, v59
	v_pk_add_f32 v[52:53], v[52:53], v[84:85]
	v_cvt_pk_bf16_f32 v91, v58, v59
	v_fmac_f32_e32 v57, v58, v58
	v_pk_add_f32 v[58:59], v[50:51], v[82:83]
	v_mul_f32_e32 v50, v53, v53
	v_mul_f32_e32 v51, v55, v55
	v_cvt_pk_bf16_f32 v89, v62, v63
	v_add_f32_e32 v62, v57, v56
	v_pk_add_f32 v[56:57], v[48:49], v[80:81]
	v_fmac_f32_e32 v50, v52, v52
	v_fmac_f32_e32 v51, v54, v54
	v_add_f32_e32 v50, v50, v51
	v_mul_f32_e32 v51, v57, v57
	v_fmac_f32_e32 v51, v56, v56
	v_add_f32_e32 v50, v50, v51
	v_mul_f32_e32 v51, v59, v59
	v_fmac_f32_e32 v51, v58, v58
	v_add_f32_e32 v50, v51, v50
	v_add_f32_e32 v62, v62, v50
	ds_bpermute_b32 v63, v178, v62
	v_lshl_add_u64 v[60:61], v[98:99], 0, v[160:161]
	v_lshl_add_u64 v[92:93], v[100:101], 1, s[24:25]
	v_lshl_add_u64 v[48:49], v[60:61], 2, s[48:49]
	global_store_dwordx4 v[92:93], v[88:91], off
	global_store_dwordx4 v[48:49], v[52:55], off nt
	global_store_dwordx4 v[48:49], v[56:59], off offset:16 nt
	s_waitcnt lgkmcnt(0)
	v_add_f32_e32 v48, v62, v63
	ds_bpermute_b32 v49, v179, v48
	v_cvt_pk_bf16_f32 v51, v54, v55
	v_lshl_add_u64 v[54:55], v[60:61], 1, s[24:25]
	v_cvt_pk_bf16_f32 v50, v52, v53
	v_cvt_pk_bf16_f32 v52, v56, v57
	v_cvt_pk_bf16_f32 v53, v58, v59
	global_store_dwordx4 v[54:55], v[50:53], off
	s_and_saveexec_b64 s[0:1], vcc
	s_cbranch_execz .LBB0_470
	v_lshl_add_u64 v[50:51], v[112:113], 2, s[10:11]
	s_waitcnt lgkmcnt(0)
	v_add_f32_e32 v48, v48, v49
	global_atomic_add_f32 v[50:51], v48, off
; #define EPI_IT_ROW(it) EPI_ROW((it) >> 2, (it) & 3)
; #define EPI_PACK8(v0, v1) (u32x4){pk2((v0)[0], (v0)[1]), pk2((v0)[2], (v0)[3]), pk2((v1)[0], (v1)[1]), pk2((v1)[2], (v1)[3])}
;     __device__ __forceinline__ void operator()(AccRef acc, const Unit& u, int wr, int wc, int fr, int fq) const {
;     ...
;         for (int it = 0; it < 8; ++it) { const int ai = it >> 2, m = it & 3, row = EPI_IT_ROW(it);
;             if (it + 1 < 8) {
; #pragma unroll
;                 for (int bj = 0; bj < 2; ++bj) { const size_t p = (size_t)EPI_IT_ROW(it + 1) * DM + EPI_COL(bj); xn[bj][0] = *(const f32x4*)(xin + p); xn[bj][1] = *(const f32x4*)(xin + p + 4); } }
;             float q = 0.f;
; #pragma unroll
;             for (int bj = 0; bj < 2; ++bj) { const size_t p = (size_t)row * DM + EPI_COL(bj);
;                 const f32x4 x0 = xc[bj][0] + acc[ai][bj][m][0], x1 = xc[bj][1] + acc[ai][bj][m][1];
;                 __builtin_nontemporal_store(x0, (f32x4*)(xout + p)); __builtin_nontemporal_store(x1, (f32x4*)(xout + p + 4));
;                 *(u32x4*)(xb + p) = EPI_PACK8(x0, x1);
;                 q += EPI_SQ8(x0, x1); }
;             q += __shfl_xor(q, 16); q += __shfl_xor(q, 32);
;             if (fq == 0) atomicAdd(ssout + row, q);
; #pragma unroll
;             for (int bj = 0; bj < 2; ++bj) { xc[bj][0] = xn[bj][0]; xc[bj][1] = xn[bj][1]; } }
.LBB0_470:
	s_or_b64 exec, exec, s[0:1]
	v_add_u32_e32 v80, 0xa0, v164
	v_ashrrev_i32_e32 v81, 31, v80
	s_waitcnt lgkmcnt(0)
	v_lshlrev_b64 v[48:49], 12, v[80:81]
	v_lshl_add_u64 v[48:49], s[16:17], 0, v[48:49]
	v_lshl_add_u64 v[50:51], v[162:163], 2, v[48:49]
	v_lshl_add_u64 v[52:53], v[160:161], 2, v[48:49]
	global_load_dwordx4 v[56:59], v[50:51], off offset:16 nt
	global_load_dwordx4 v[60:63], v[50:51], off nt
	s_nop 0
	global_load_dwordx4 v[48:51], v[52:53], off offset:16 nt
	s_nop 0
	global_load_dwordx4 v[52:55], v[52:53], off nt
	v_lshlrev_b64 v[82:83], 10, v[96:97]
	v_lshl_add_u64 v[84:85], v[82:83], 0, v[162:163]
	s_waitcnt vmcnt(12)
	v_pk_add_f32 v[46:47], v[46:47], v[78:79]
	v_pk_add_f32 v[44:45], v[44:45], v[76:77]
	v_pk_add_f32 v[40:41], v[40:41], v[72:73]
	v_lshl_add_u64 v[72:73], v[84:85], 2, s[48:49]
	v_pk_add_f32 v[42:43], v[42:43], v[74:75]
	global_store_dwordx4 v[72:73], v[44:47], off nt
	global_store_dwordx4 v[72:73], v[40:43], off offset:16 nt
	v_cvt_pk_bf16_f32 v72, v44, v45
	v_cvt_pk_bf16_f32 v74, v40, v41
	s_waitcnt vmcnt(12)
	v_pk_add_f32 v[38:39], v[38:39], v[70:71]
	v_mul_f32_e32 v45, v45, v45
	v_fmac_f32_e32 v45, v44, v44
	v_mul_f32_e32 v44, v47, v47
	v_fmac_f32_e32 v44, v46, v46
	v_mul_f32_e32 v41, v41, v41
	v_add_f32_e32 v44, v45, v44
	v_fmac_f32_e32 v41, v40, v40
	v_add_f32_e32 v40, v44, v41
	v_mul_f32_e32 v41, v43, v43
	v_pk_add_f32 v[36:37], v[36:37], v[68:69]
	v_cvt_pk_bf16_f32 v75, v42, v43
	v_fmac_f32_e32 v41, v42, v42
	v_pk_add_f32 v[42:43], v[34:35], v[66:67]
	v_mul_f32_e32 v34, v37, v37
	v_mul_f32_e32 v35, v39, v39
	v_cvt_pk_bf16_f32 v73, v46, v47
	v_add_f32_e32 v46, v41, v40
	v_pk_add_f32 v[40:41], v[32:33], v[64:65]
	v_fmac_f32_e32 v34, v36, v36
	v_fmac_f32_e32 v35, v38, v38
	v_add_f32_e32 v34, v34, v35
	v_mul_f32_e32 v35, v41, v41
	v_fmac_f32_e32 v35, v40, v40
	v_add_f32_e32 v34, v34, v35
	v_mul_f32_e32 v35, v43, v43
	v_fmac_f32_e32 v35, v42, v42
	v_add_f32_e32 v34, v35, v34
	v_add_f32_e32 v46, v46, v34
	ds_bpermute_b32 v47, v178, v46
	v_lshl_add_u64 v[44:45], v[82:83], 0, v[160:161]
	v_lshl_add_u64 v[76:77], v[84:85], 1, s[24:25]
	v_lshl_add_u64 v[32:33], v[44:45], 2, s[48:49]
	global_store_dwordx4 v[76:77], v[72:75], off
	global_store_dwordx4 v[32:33], v[36:39], off nt
	global_store_dwordx4 v[32:33], v[40:43], off offset:16 nt
	s_waitcnt lgkmcnt(0)
	v_add_f32_e32 v32, v46, v47
	ds_bpermute_b32 v33, v179, v32
	v_cvt_pk_bf16_f32 v35, v38, v39
	v_lshl_add_u64 v[38:39], v[44:45], 1, s[24:25]
	v_cvt_pk_bf16_f32 v34, v36, v37
	v_cvt_pk_bf16_f32 v36, v40, v41
	v_cvt_pk_bf16_f32 v37, v42, v43
	global_store_dwordx4 v[38:39], v[34:37], off
	s_and_saveexec_b64 s[0:1], vcc
	s_cbranch_execz .LBB0_472
	v_lshl_add_u64 v[34:35], v[96:97], 2, s[10:11]
	s_waitcnt lgkmcnt(0)
	v_add_f32_e32 v32, v32, v33
	global_atomic_add_f32 v[34:35], v32, off
.LBB0_472:
	s_or_b64 exec, exec, s[0:1]
	v_add_u32_e32 v64, 0xb0, v164
	v_ashrrev_i32_e32 v65, 31, v64
	s_waitcnt lgkmcnt(0)
	v_lshlrev_b64 v[32:33], 12, v[64:65]
	v_lshl_add_u64 v[32:33], s[16:17], 0, v[32:33]
	v_lshl_add_u64 v[34:35], v[162:163], 2, v[32:33]
	v_lshl_add_u64 v[36:37], v[160:161], 2, v[32:33]
	global_load_dwordx4 v[40:43], v[34:35], off offset:16 nt
	global_load_dwordx4 v[44:47], v[34:35], off nt
	s_nop 0
	global_load_dwordx4 v[32:35], v[36:37], off offset:16 nt
	s_nop 0
	global_load_dwordx4 v[36:39], v[36:37], off nt
	v_lshlrev_b64 v[66:67], 10, v[80:81]
	v_lshl_add_u64 v[68:69], v[66:67], 0, v[162:163]
	s_waitcnt vmcnt(12)
	v_pk_add_f32 v[30:31], v[30:31], v[62:63]
	v_pk_add_f32 v[28:29], v[28:29], v[60:61]
	v_pk_add_f32 v[24:25], v[24:25], v[56:57]
	v_lshl_add_u64 v[56:57], v[68:69], 2, s[48:49]
	v_pk_add_f32 v[26:27], v[26:27], v[58:59]
	global_store_dwordx4 v[56:57], v[28:31], off nt
	global_store_dwordx4 v[56:57], v[24:27], off offset:16 nt
	v_cvt_pk_bf16_f32 v56, v28, v29
	v_cvt_pk_bf16_f32 v58, v24, v25
	s_waitcnt vmcnt(12)
	v_pk_add_f32 v[22:23], v[22:23], v[54:55]
	v_mul_f32_e32 v29, v29, v29
	v_fmac_f32_e32 v29, v28, v28
	v_mul_f32_e32 v28, v31, v31
	v_fmac_f32_e32 v28, v30, v30
	v_mul_f32_e32 v25, v25, v25
	v_add_f32_e32 v28, v29, v28
	v_fmac_f32_e32 v25, v24, v24
	v_add_f32_e32 v24, v28, v25
	v_mul_f32_e32 v25, v27, v27
	v_pk_add_f32 v[20:21], v[20:21], v[52:53]
	v_cvt_pk_bf16_f32 v59, v26, v27
	v_fmac_f32_e32 v25, v26, v26
	v_pk_add_f32 v[26:27], v[18:19], v[50:51]
	v_mul_f32_e32 v18, v21, v21
	v_mul_f32_e32 v19, v23, v23
	v_cvt_pk_bf16_f32 v57, v30, v31
	v_add_f32_e32 v30, v25, v24
	v_pk_add_f32 v[24:25], v[16:17], v[48:49]
	v_fmac_f32_e32 v18, v20, v20
	v_fmac_f32_e32 v19, v22, v22
	v_add_f32_e32 v18, v18, v19
	v_mul_f32_e32 v19, v25, v25
	v_fmac_f32_e32 v19, v24, v24
	v_add_f32_e32 v18, v18, v19
	v_mul_f32_e32 v19, v27, v27
	v_fmac_f32_e32 v19, v26, v26
	v_add_f32_e32 v18, v19, v18
	v_add_f32_e32 v30, v30, v18
	ds_bpermute_b32 v31, v178, v30
	v_lshl_add_u64 v[28:29], v[66:67], 0, v[160:161]
	v_lshl_add_u64 v[60:61], v[68:69], 1, s[24:25]
	v_lshl_add_u64 v[16:17], v[28:29], 2, s[48:49]
	global_store_dwordx4 v[60:61], v[56:59], off
	global_store_dwordx4 v[16:17], v[20:23], off nt
	global_store_dwordx4 v[16:17], v[24:27], off offset:16 nt
	s_waitcnt lgkmcnt(0)
	v_add_f32_e32 v16, v30, v31
	ds_bpermute_b32 v17, v179, v16
	v_cvt_pk_bf16_f32 v19, v22, v23
	v_lshl_add_u64 v[22:23], v[28:29], 1, s[24:25]
	v_cvt_pk_bf16_f32 v18, v20, v21
	v_cvt_pk_bf16_f32 v20, v24, v25
	v_cvt_pk_bf16_f32 v21, v26, v27
	global_store_dwordx4 v[22:23], v[18:21], off
	s_and_saveexec_b64 s[0:1], vcc
	s_cbranch_execz .LBB0_474
	v_lshl_add_u64 v[18:19], v[80:81], 2, s[10:11]
	s_waitcnt lgkmcnt(0)
	v_add_f32_e32 v16, v16, v17
	global_atomic_add_f32 v[18:19], v16, off

; #define EPI_IT_ROW(it) EPI_ROW((it) >> 2, (it) & 3)
; #define EPI_PACK8(v0, v1) (u32x4){pk2((v0)[0], (v0)[1]), pk2((v0)[2], (v0)[3]), pk2((v1)[0], (v1)[1]), pk2((v1)[2], (v1)[3])}
;     __device__ __forceinline__ void operator()(AccRef acc, const Unit& u, int wr, int wc, int fr, int fq) const {
;     ...
;         for (int bj = 0; bj < 2; ++bj) { const size_t p = (size_t)EPI_IT_ROW(0) * DM + EPI_COL(bj); xc[bj][0] = *(const f32x4*)(xin + p); xc[bj][1] = *(const f32x4*)(xin + p + 4); }
; #pragma unroll
;         for (int it = 0; it < 8; ++it) { const int ai = it >> 2, m = it & 3, row = EPI_IT_ROW(it);
;             if (it + 1 < 8) {
; #pragma unroll
;                 for (int bj = 0; bj < 2; ++bj) { const size_t p = (size_t)EPI_IT_ROW(it + 1) * DM + EPI_COL(bj); xn[bj][0] = *(const f32x4*)(xin + p); xn[bj][1] = *(const f32x4*)(xin + p + 4); } }
;             float q = 0.f;
; #pragma unroll
;             for (int bj = 0; bj < 2; ++bj) { const size_t p = (size_t)row * DM + EPI_COL(bj);
;                 const f32x4 x0 = xc[bj][0] + acc[ai][bj][m][0], x1 = xc[bj][1] + acc[ai][bj][m][1];
;                 __builtin_nontemporal_store(x0, (f32x4*)(xout + p)); __builtin_nontemporal_store(x1, (f32x4*)(xout + p + 4));
;                 *(u32x4*)(xb + p) = EPI_PACK8(x0, x1);
;                 q += EPI_SQ8(x0, x1); }
;             q += __shfl_xor(q, 16); q += __shfl_xor(q, 32);
;             if (fq == 0) atomicAdd(ssout + row, q);
; #pragma unroll
;             for (int bj = 0; bj < 2; ++bj) { xc[bj][0] = xn[bj][0]; xc[bj][1] = xn[bj][1]; } }
.LBB0_795:
	s_lshl_b32 s0, s74, 8
	v_mov_b32_e32 v128, v180
	v_mov_b32_e32 v186, v177
	s_add_i32 s0, s0, s56
	v_and_b32_e32 v202, 64, v185
	v_add_u32_e32 v164, s0, v128
	s_lshl_b32 s0, s73, 8
	s_or_b32 s0, s0, s57
	v_ashrrev_i32_e32 v165, 31, v164
	v_lshl_add_u32 v162, v186, 3, s0
	v_lshlrev_b64 v[128:129], 12, v[164:165]
	v_ashrrev_i32_e32 v163, 31, v162
	v_add_u32_e32 v160, 0x80, v162
	v_lshl_add_u64 v[128:129], s[48:49], 0, v[128:129]
	v_lshlrev_b64 v[130:131], 2, v[162:163]
	v_ashrrev_i32_e32 v161, 31, v160
	v_lshl_add_u64 v[178:179], v[128:129], 0, v[130:131]
	v_lshlrev_b64 v[132:133], 2, v[160:161]
	global_load_dwordx4 v[170:173], v[178:179], off offset:16 nt
	global_load_dwordx4 v[188:191], v[178:179], off nt
	v_lshl_add_u64 v[200:201], v[128:129], 0, v[132:133]
	global_load_dwordx4 v[192:195], v[200:201], off nt
	global_load_dwordx4 v[196:199], v[200:201], off offset:16 nt
	v_add_u32_e32 v166, 16, v164
	v_ashrrev_i32_e32 v167, 31, v166
	v_lshlrev_b64 v[128:129], 12, v[166:167]
	v_lshl_add_u64 v[128:129], s[48:49], 0, v[128:129]
	v_lshl_add_u64 v[174:175], v[128:129], 0, v[130:131]
	v_lshl_add_u64 v[168:169], v[128:129], 0, v[132:133]
	global_load_dwordx4 v[136:139], v[174:175], off offset:16 nt
	global_load_dwordx4 v[140:143], v[174:175], off nt
	global_load_dwordx4 v[128:131], v[168:169], off offset:16 nt
	global_load_dwordx4 v[132:135], v[168:169], off nt
	v_xor_b32_e32 v187, 16, v185
	v_add_u32_e32 v202, 64, v202
	v_cmp_lt_i32_e64 s[0:1], v187, v202
	v_cmp_eq_u32_e32 vcc, 0, v186
	v_xor_b32_e32 v203, 32, v185
	v_cndmask_b32_e64 v186, v185, v187, s[0:1]
	v_lshlrev_b32_e32 v186, 2, v186
	v_cmp_lt_i32_e64 s[0:1], v203, v202
	s_waitcnt vmcnt(0)
	v_pk_add_f32 v[122:123], v[122:123], v[172:173]
	v_pk_add_f32 v[126:127], v[126:127], v[190:191]
	v_pk_add_f32 v[124:125], v[124:125], v[188:189]
	v_pk_add_f32 v[118:119], v[118:119], v[194:195]
	v_pk_add_f32 v[116:117], v[116:117], v[192:193]
	v_pk_add_f32 v[120:121], v[120:121], v[170:171]
	v_pk_add_f32 v[170:171], v[112:113], v[196:197]
	global_store_dwordx4 v[178:179], v[124:127], off nt
	global_store_dwordx4 v[178:179], v[120:123], off offset:16 nt
	v_cvt_pk_bf16_f32 v112, v124, v125
	v_cvt_pk_bf16_f32 v113, v126, v127
	v_mul_f32_e32 v178, v117, v117
	v_mul_f32_e32 v125, v125, v125
	v_mul_f32_e32 v127, v127, v127
	v_mul_f32_e32 v179, v119, v119
	v_pk_add_f32 v[172:173], v[114:115], v[198:199]
	v_cvt_pk_bf16_f32 v114, v120, v121
	v_cvt_pk_bf16_f32 v115, v122, v123
	v_mul_f32_e32 v121, v121, v121
	v_mul_f32_e32 v123, v123, v123
	v_mul_f32_e32 v189, v171, v171
	v_fmac_f32_e32 v125, v124, v124
	v_fmac_f32_e32 v127, v126, v126
	v_fmac_f32_e32 v178, v116, v116
	v_fmac_f32_e32 v179, v118, v118
	v_mul_f32_e32 v190, v173, v173
	v_fmac_f32_e32 v121, v120, v120
	v_fmac_f32_e32 v123, v122, v122
	v_fmac_f32_e32 v189, v170, v170
	v_add_f32_e32 v120, v125, v127
	v_add_f32_e32 v122, v178, v179
	v_fmac_f32_e32 v190, v172, v172
	v_add_f32_e32 v120, v120, v121
	v_add_f32_e32 v121, v122, v189
	v_add_f32_e32 v120, v123, v120
	v_add_f32_e32 v121, v190, v121
	v_add_f32_e32 v120, v120, v121
	ds_bpermute_b32 v121, v186, v120
	v_cndmask_b32_e64 v187, v185, v203, s[0:1]
	v_lshlrev_b64 v[202:203], 10, v[164:165]
	v_lshl_add_u64 v[204:205], v[202:203], 0, v[162:163]
	v_lshl_add_u64 v[204:205], v[204:205], 1, s[30:31]
	global_store_dwordx4 v[204:205], v[112:115], off
	global_store_dwordx4 v[200:201], v[116:119], off nt
	global_store_dwordx4 v[200:201], v[170:173], off offset:16 nt
	s_waitcnt lgkmcnt(0)
	v_add_f32_e32 v112, v120, v121
	v_lshlrev_b32_e32 v187, 2, v187
	ds_bpermute_b32 v113, v187, v112
	v_lshl_add_u64 v[202:203], v[202:203], 0, v[160:161]
	v_lshl_add_u64 v[114:115], v[202:203], 1, s[30:31]
	v_cvt_pk_bf16_f32 v188, v116, v117
	v_cvt_pk_bf16_f32 v189, v118, v119
	v_cvt_pk_bf16_f32 v190, v170, v171
	v_cvt_pk_bf16_f32 v191, v172, v173
	global_store_dwordx4 v[114:115], v[188:191], off
	s_and_saveexec_b64 s[0:1], vcc
	s_cbranch_execz .LBB0_797
	v_lshl_add_u64 v[114:115], v[164:165], 2, s[12:13]
	s_waitcnt lgkmcnt(0)
	v_add_f32_e32 v112, v112, v113
	global_atomic_add_f32 v[114:115], v112, off
.LBB0_797:
	s_or_b64 exec, exec, s[0:1]
	v_add_u32_e32 v170, 32, v164
	v_ashrrev_i32_e32 v171, 31, v170
	s_waitcnt lgkmcnt(0)
	v_lshlrev_b64 v[112:113], 12, v[170:171]
	v_lshl_add_u64 v[112:113], s[48:49], 0, v[112:113]
	v_lshl_add_u64 v[178:179], v[162:163], 2, v[112:113]
	v_lshl_add_u64 v[172:173], v[160:161], 2, v[112:113]
	global_load_dwordx4 v[120:123], v[178:179], off offset:16 nt
	global_load_dwordx4 v[124:127], v[178:179], off nt
	global_load_dwordx4 v[112:115], v[172:173], off offset:16 nt
	global_load_dwordx4 v[116:119], v[172:173], off nt
	v_pk_add_f32 v[110:111], v[110:111], v[142:143]
	v_pk_add_f32 v[108:109], v[108:109], v[140:141]
	v_pk_add_f32 v[106:107], v[106:107], v[138:139]
	v_pk_add_f32 v[104:105], v[104:105], v[136:137]
	global_store_dwordx4 v[174:175], v[108:111], off nt
	global_store_dwordx4 v[174:175], v[104:107], off offset:16 nt
	v_cvt_pk_bf16_f32 v136, v108, v109
	v_cvt_pk_bf16_f32 v138, v104, v105
	v_pk_add_f32 v[102:103], v[102:103], v[134:135]
	v_mul_f32_e32 v109, v109, v109
	v_fmac_f32_e32 v109, v108, v108
	v_mul_f32_e32 v108, v111, v111
	v_fmac_f32_e32 v108, v110, v110
	v_mul_f32_e32 v105, v105, v105
	v_add_f32_e32 v108, v109, v108
	v_fmac_f32_e32 v105, v104, v104
	v_add_f32_e32 v104, v108, v105
	v_mul_f32_e32 v105, v107, v107
	v_fmac_f32_e32 v105, v106, v106
	v_pk_add_f32 v[100:101], v[100:101], v[132:133]
	v_cvt_pk_bf16_f32 v137, v110, v111
	v_add_f32_e32 v110, v105, v104
	v_pk_add_f32 v[104:105], v[96:97], v[128:129]
	v_mul_f32_e32 v96, v101, v101
	v_mul_f32_e32 v97, v103, v103
	v_fmac_f32_e32 v96, v100, v100
	v_fmac_f32_e32 v97, v102, v102
	v_add_f32_e32 v96, v96, v97
	v_mul_f32_e32 v97, v105, v105
	v_cvt_pk_bf16_f32 v139, v106, v107
	v_pk_add_f32 v[106:107], v[98:99], v[130:131]
	v_fmac_f32_e32 v97, v104, v104
	v_add_f32_e32 v96, v96, v97
	v_mul_f32_e32 v97, v107, v107
	v_fmac_f32_e32 v97, v106, v106
	v_add_f32_e32 v96, v97, v96
	v_add_f32_e32 v96, v110, v96
	ds_bpermute_b32 v97, v186, v96
	v_lshlrev_b64 v[188:189], 10, v[166:167]
	v_lshl_add_u64 v[190:191], v[188:189], 0, v[162:163]
	v_lshl_add_u64 v[140:141], v[190:191], 1, s[30:31]
	v_lshl_add_u64 v[108:109], v[188:189], 0, v[160:161]
	s_waitcnt lgkmcnt(0)
	v_add_f32_e32 v96, v96, v97
	ds_bpermute_b32 v97, v187, v96
	global_store_dwordx4 v[140:141], v[136:139], off
	global_store_dwordx4 v[168:169], v[100:103], off nt
	global_store_dwordx4 v[168:169], v[104:107], off offset:16 nt
	v_cvt_pk_bf16_f32 v99, v102, v103
	v_cvt_pk_bf16_f32 v98, v100, v101
	s_nop 0
	v_lshl_add_u64 v[102:103], v[108:109], 1, s[30:31]
	v_cvt_pk_bf16_f32 v100, v104, v105
	v_cvt_pk_bf16_f32 v101, v106, v107
	global_store_dwordx4 v[102:103], v[98:101], off
	s_and_saveexec_b64 s[0:1], vcc
	s_cbranch_execz .LBB0_799
	v_lshl_add_u64 v[98:99], v[166:167], 2, s[12:13]
	s_waitcnt lgkmcnt(0)
	v_add_f32_e32 v96, v96, v97
	global_atomic_add_f32 v[98:99], v96, off
; #define EPI_IT_ROW(it) EPI_ROW((it) >> 2, (it) & 3)
; #define EPI_PACK8(v0, v1) (u32x4){pk2((v0)[0], (v0)[1]), pk2((v0)[2], (v0)[3]), pk2((v1)[0], (v1)[1]), pk2((v1)[2], (v1)[3])}
;     __device__ __forceinline__ void operator()(AccRef acc, const Unit& u, int wr, int wc, int fr, int fq) const {
;     ...
;         for (int it = 0; it < 8; ++it) { const int ai = it >> 2, m = it & 3, row = EPI_IT_ROW(it);
;             if (it + 1 < 8) {
; #pragma unroll
;                 for (int bj = 0; bj < 2; ++bj) { const size_t p = (size_t)EPI_IT_ROW(it + 1) * DM + EPI_COL(bj); xn[bj][0] = *(const f32x4*)(xin + p); xn[bj][1] = *(const f32x4*)(xin + p + 4); } }
;             float q = 0.f;
; #pragma unroll
;             for (int bj = 0; bj < 2; ++bj) { const size_t p = (size_t)row * DM + EPI_COL(bj);
;                 const f32x4 x0 = xc[bj][0] + acc[ai][bj][m][0], x1 = xc[bj][1] + acc[ai][bj][m][1];
;                 __builtin_nontemporal_store(x0, (f32x4*)(xout + p)); __builtin_nontemporal_store(x1, (f32x4*)(xout + p + 4));
;                 *(u32x4*)(xb + p) = EPI_PACK8(x0, x1);
;                 q += EPI_SQ8(x0, x1); }
;             q += __shfl_xor(q, 16); q += __shfl_xor(q, 32);
;             if (fq == 0) atomicAdd(ssout + row, q);
; #pragma unroll
;             for (int bj = 0; bj < 2; ++bj) { xc[bj][0] = xn[bj][0]; xc[bj][1] = xn[bj][1]; } }
.LBB0_799:
	s_or_b64 exec, exec, s[0:1]
	v_add_u32_e32 v128, 48, v164
	v_ashrrev_i32_e32 v129, 31, v128
	s_waitcnt lgkmcnt(0)
	v_lshlrev_b64 v[96:97], 12, v[128:129]
	v_lshl_add_u64 v[96:97], s[48:49], 0, v[96:97]
	v_lshl_add_u64 v[132:133], v[162:163], 2, v[96:97]
	v_lshl_add_u64 v[130:131], v[160:161], 2, v[96:97]
	global_load_dwordx4 v[104:107], v[132:133], off offset:16 nt
	global_load_dwordx4 v[108:111], v[132:133], off nt
	global_load_dwordx4 v[96:99], v[130:131], off offset:16 nt
	global_load_dwordx4 v[100:103], v[130:131], off nt
	s_waitcnt vmcnt(12)
	v_pk_add_f32 v[94:95], v[94:95], v[126:127]
	v_pk_add_f32 v[92:93], v[92:93], v[124:125]
	v_pk_add_f32 v[90:91], v[90:91], v[122:123]
	v_pk_add_f32 v[88:89], v[88:89], v[120:121]
	global_store_dwordx4 v[178:179], v[92:95], off nt
	global_store_dwordx4 v[178:179], v[88:91], off offset:16 nt
	v_cvt_pk_bf16_f32 v120, v92, v93
	v_cvt_pk_bf16_f32 v122, v88, v89
	s_waitcnt vmcnt(12)
	v_pk_add_f32 v[86:87], v[86:87], v[118:119]
	v_mul_f32_e32 v93, v93, v93
	v_fmac_f32_e32 v93, v92, v92
	v_mul_f32_e32 v92, v95, v95
	v_fmac_f32_e32 v92, v94, v94
	v_mul_f32_e32 v89, v89, v89
	v_add_f32_e32 v92, v93, v92
	v_fmac_f32_e32 v89, v88, v88
	v_add_f32_e32 v88, v92, v89
	v_mul_f32_e32 v89, v91, v91
	v_fmac_f32_e32 v89, v90, v90
	v_pk_add_f32 v[84:85], v[84:85], v[116:117]
	v_cvt_pk_bf16_f32 v121, v94, v95
	v_add_f32_e32 v94, v89, v88
	v_pk_add_f32 v[88:89], v[80:81], v[112:113]
	v_mul_f32_e32 v80, v85, v85
	v_mul_f32_e32 v81, v87, v87
	v_fmac_f32_e32 v80, v84, v84
	v_fmac_f32_e32 v81, v86, v86
	v_add_f32_e32 v80, v80, v81
	v_mul_f32_e32 v81, v89, v89
	v_cvt_pk_bf16_f32 v123, v90, v91
	v_pk_add_f32 v[90:91], v[82:83], v[114:115]
	v_fmac_f32_e32 v81, v88, v88
	v_add_f32_e32 v80, v80, v81
	v_mul_f32_e32 v81, v91, v91
	v_fmac_f32_e32 v81, v90, v90
	v_add_f32_e32 v80, v81, v80
	v_add_f32_e32 v80, v94, v80
	ds_bpermute_b32 v81, v186, v80
	v_lshlrev_b64 v[134:135], 10, v[170:171]
	v_lshl_add_u64 v[136:137], v[134:135], 0, v[162:163]
	v_lshl_add_u64 v[124:125], v[136:137], 1, s[30:31]
	v_lshl_add_u64 v[92:93], v[134:135], 0, v[160:161]
	s_waitcnt lgkmcnt(0)
	v_add_f32_e32 v80, v80, v81
	ds_bpermute_b32 v81, v187, v80
	global_store_dwordx4 v[124:125], v[120:123], off
	global_store_dwordx4 v[172:173], v[84:87], off nt
	global_store_dwordx4 v[172:173], v[88:91], off offset:16 nt
	v_cvt_pk_bf16_f32 v83, v86, v87
	v_cvt_pk_bf16_f32 v82, v84, v85
	s_nop 0
	v_lshl_add_u64 v[86:87], v[92:93], 1, s[30:31]
	v_cvt_pk_bf16_f32 v84, v88, v89
	v_cvt_pk_bf16_f32 v85, v90, v91
	global_store_dwordx4 v[86:87], v[82:85], off
	s_and_saveexec_b64 s[0:1], vcc
	s_cbranch_execz .LBB0_801
	v_lshl_add_u64 v[82:83], v[170:171], 2, s[12:13]
	s_waitcnt lgkmcnt(0)
	v_add_f32_e32 v80, v80, v81
	global_atomic_add_f32 v[82:83], v80, off
.LBB0_801:
	s_or_b64 exec, exec, s[0:1]
	v_add_u32_e32 v112, 0x80, v164
	v_ashrrev_i32_e32 v113, 31, v112
	s_waitcnt lgkmcnt(0)
	v_lshlrev_b64 v[80:81], 12, v[112:113]
	v_lshl_add_u64 v[80:81], s[48:49], 0, v[80:81]
	v_lshl_add_u64 v[116:117], v[162:163], 2, v[80:81]
	v_lshl_add_u64 v[114:115], v[160:161], 2, v[80:81]
	global_load_dwordx4 v[88:91], v[116:117], off offset:16 nt
	global_load_dwordx4 v[92:95], v[116:117], off nt
	global_load_dwordx4 v[80:83], v[114:115], off offset:16 nt
	global_load_dwordx4 v[84:87], v[114:115], off nt
	s_waitcnt vmcnt(12)
	v_pk_add_f32 v[78:79], v[78:79], v[110:111]
	v_pk_add_f32 v[76:77], v[76:77], v[108:109]
	v_pk_add_f32 v[74:75], v[74:75], v[106:107]
	v_pk_add_f32 v[72:73], v[72:73], v[104:105]
	global_store_dwordx4 v[132:133], v[76:79], off nt
	global_store_dwordx4 v[132:133], v[72:75], off offset:16 nt
	v_cvt_pk_bf16_f32 v104, v76, v77
	v_cvt_pk_bf16_f32 v106, v72, v73
	s_waitcnt vmcnt(12)
	v_pk_add_f32 v[70:71], v[70:71], v[102:103]
	v_mul_f32_e32 v77, v77, v77
	v_fmac_f32_e32 v77, v76, v76
	v_mul_f32_e32 v76, v79, v79
	v_fmac_f32_e32 v76, v78, v78
	v_mul_f32_e32 v73, v73, v73
	v_add_f32_e32 v76, v77, v76
	v_fmac_f32_e32 v73, v72, v72
	v_add_f32_e32 v72, v76, v73
	v_mul_f32_e32 v73, v75, v75
	v_fmac_f32_e32 v73, v74, v74
	v_pk_add_f32 v[68:69], v[68:69], v[100:101]
	v_cvt_pk_bf16_f32 v105, v78, v79
	v_add_f32_e32 v78, v73, v72
	v_pk_add_f32 v[72:73], v[64:65], v[96:97]
	v_mul_f32_e32 v64, v69, v69
	v_mul_f32_e32 v65, v71, v71
	v_fmac_f32_e32 v64, v68, v68
	v_fmac_f32_e32 v65, v70, v70
	v_add_f32_e32 v64, v64, v65
	v_mul_f32_e32 v65, v73, v73
	v_cvt_pk_bf16_f32 v107, v74, v75
	v_pk_add_f32 v[74:75], v[66:67], v[98:99]
	v_fmac_f32_e32 v65, v72, v72
	v_add_f32_e32 v64, v64, v65
	v_mul_f32_e32 v65, v75, v75
	v_fmac_f32_e32 v65, v74, v74
	v_add_f32_e32 v64, v65, v64
	v_add_f32_e32 v64, v78, v64
	ds_bpermute_b32 v65, v186, v64
	v_lshlrev_b64 v[118:119], 10, v[128:129]
	v_lshl_add_u64 v[120:121], v[118:119], 0, v[162:163]
	v_lshl_add_u64 v[108:109], v[120:121], 1, s[30:31]
	v_lshl_add_u64 v[76:77], v[118:119], 0, v[160:161]
	s_waitcnt lgkmcnt(0)
	v_add_f32_e32 v64, v64, v65
	ds_bpermute_b32 v65, v187, v64
	global_store_dwordx4 v[108:109], v[104:107], off
	global_store_dwordx4 v[130:131], v[68:71], off nt
	global_store_dwordx4 v[130:131], v[72:75], off offset:16 nt
	v_cvt_pk_bf16_f32 v67, v70, v71
	v_cvt_pk_bf16_f32 v66, v68, v69
	s_nop 0
	v_lshl_add_u64 v[70:71], v[76:77], 1, s[30:31]
	v_cvt_pk_bf16_f32 v68, v72, v73
	v_cvt_pk_bf16_f32 v69, v74, v75
	global_store_dwordx4 v[70:71], v[66:69], off
	s_and_saveexec_b64 s[0:1], vcc
	s_cbranch_execz .LBB0_803
	v_lshl_add_u64 v[66:67], v[128:129], 2, s[12:13]
	s_waitcnt lgkmcnt(0)
	v_add_f32_e32 v64, v64, v65
	global_atomic_add_f32 v[66:67], v64, off
; #define EPI_IT_ROW(it) EPI_ROW((it) >> 2, (it) & 3)
; #define EPI_PACK8(v0, v1) (u32x4){pk2((v0)[0], (v0)[1]), pk2((v0)[2], (v0)[3]), pk2((v1)[0], (v1)[1]), pk2((v1)[2], (v1)[3])}
;     __device__ __forceinline__ void operator()(AccRef acc, const Unit& u, int wr, int wc, int fr, int fq) const {
;     ...
;         for (int it = 0; it < 8; ++it) { const int ai = it >> 2, m = it & 3, row = EPI_IT_ROW(it);
;             if (it + 1 < 8) {
; #pragma unroll
;                 for (int bj = 0; bj < 2; ++bj) { const size_t p = (size_t)EPI_IT_ROW(it + 1) * DM + EPI_COL(bj); xn[bj][0] = *(const f32x4*)(xin + p); xn[bj][1] = *(const f32x4*)(xin + p + 4); } }
;             float q = 0.f;
; #pragma unroll
;             for (int bj = 0; bj < 2; ++bj) { const size_t p = (size_t)row * DM + EPI_COL(bj);
;                 const f32x4 x0 = xc[bj][0] + acc[ai][bj][m][0], x1 = xc[bj][1] + acc[ai][bj][m][1];
;                 __builtin_nontemporal_store(x0, (f32x4*)(xout + p)); __builtin_nontemporal_store(x1, (f32x4*)(xout + p + 4));
;                 *(u32x4*)(xb + p) = EPI_PACK8(x0, x1);
;                 q += EPI_SQ8(x0, x1); }
;             q += __shfl_xor(q, 16); q += __shfl_xor(q, 32);
;             if (fq == 0) atomicAdd(ssout + row, q);
; #pragma unroll
;             for (int bj = 0; bj < 2; ++bj) { xc[bj][0] = xn[bj][0]; xc[bj][1] = xn[bj][1]; } }
.LBB0_803:
	s_or_b64 exec, exec, s[0:1]
	v_add_u32_e32 v96, 0x90, v164
	v_ashrrev_i32_e32 v97, 31, v96
	s_waitcnt lgkmcnt(0)
	v_lshlrev_b64 v[64:65], 12, v[96:97]
	v_lshl_add_u64 v[64:65], s[48:49], 0, v[64:65]
	v_lshl_add_u64 v[100:101], v[162:163], 2, v[64:65]
	v_lshl_add_u64 v[98:99], v[160:161], 2, v[64:65]
	global_load_dwordx4 v[72:75], v[100:101], off offset:16 nt
	global_load_dwordx4 v[76:79], v[100:101], off nt
	global_load_dwordx4 v[64:67], v[98:99], off offset:16 nt
	global_load_dwordx4 v[68:71], v[98:99], off nt
	s_waitcnt vmcnt(12)
	v_pk_add_f32 v[62:63], v[62:63], v[94:95]
	v_pk_add_f32 v[60:61], v[60:61], v[92:93]
	v_pk_add_f32 v[58:59], v[58:59], v[90:91]
	v_pk_add_f32 v[56:57], v[56:57], v[88:89]
	global_store_dwordx4 v[116:117], v[60:63], off nt
	global_store_dwordx4 v[116:117], v[56:59], off offset:16 nt
	v_cvt_pk_bf16_f32 v88, v60, v61
	v_cvt_pk_bf16_f32 v90, v56, v57
	s_waitcnt vmcnt(12)
	v_pk_add_f32 v[54:55], v[54:55], v[86:87]
	v_mul_f32_e32 v61, v61, v61
	v_fmac_f32_e32 v61, v60, v60
	v_mul_f32_e32 v60, v63, v63
	v_fmac_f32_e32 v60, v62, v62
	v_mul_f32_e32 v57, v57, v57
	v_add_f32_e32 v60, v61, v60
	v_fmac_f32_e32 v57, v56, v56
	v_add_f32_e32 v56, v60, v57
	v_mul_f32_e32 v57, v59, v59
	v_fmac_f32_e32 v57, v58, v58
	v_pk_add_f32 v[52:53], v[52:53], v[84:85]
	v_cvt_pk_bf16_f32 v89, v62, v63
	v_add_f32_e32 v62, v57, v56
	v_pk_add_f32 v[56:57], v[48:49], v[80:81]
	v_mul_f32_e32 v48, v53, v53
	v_mul_f32_e32 v49, v55, v55
	v_fmac_f32_e32 v48, v52, v52
	v_fmac_f32_e32 v49, v54, v54
	v_add_f32_e32 v48, v48, v49
	v_mul_f32_e32 v49, v57, v57
	v_cvt_pk_bf16_f32 v91, v58, v59
	v_pk_add_f32 v[58:59], v[50:51], v[82:83]
	v_fmac_f32_e32 v49, v56, v56
	v_add_f32_e32 v48, v48, v49
	v_mul_f32_e32 v49, v59, v59
	v_fmac_f32_e32 v49, v58, v58
	v_add_f32_e32 v48, v49, v48
	v_add_f32_e32 v48, v62, v48
	ds_bpermute_b32 v49, v186, v48
	v_lshlrev_b64 v[102:103], 10, v[112:113]
	v_lshl_add_u64 v[104:105], v[102:103], 0, v[162:163]
	v_lshl_add_u64 v[92:93], v[104:105], 1, s[30:31]
	v_lshl_add_u64 v[60:61], v[102:103], 0, v[160:161]
	s_waitcnt lgkmcnt(0)
	v_add_f32_e32 v48, v48, v49
	ds_bpermute_b32 v49, v187, v48
	global_store_dwordx4 v[92:93], v[88:91], off
	global_store_dwordx4 v[114:115], v[52:55], off nt
	global_store_dwordx4 v[114:115], v[56:59], off offset:16 nt
	v_cvt_pk_bf16_f32 v51, v54, v55
	v_cvt_pk_bf16_f32 v50, v52, v53
	s_nop 0
	v_lshl_add_u64 v[54:55], v[60:61], 1, s[30:31]
	v_cvt_pk_bf16_f32 v52, v56, v57
	v_cvt_pk_bf16_f32 v53, v58, v59
	global_store_dwordx4 v[54:55], v[50:53], off
	s_and_saveexec_b64 s[0:1], vcc
	s_cbranch_execz .LBB0_805
	v_lshl_add_u64 v[50:51], v[112:113], 2, s[12:13]
	s_waitcnt lgkmcnt(0)
	v_add_f32_e32 v48, v48, v49
	global_atomic_add_f32 v[50:51], v48, off
; #define EPI_IT_ROW(it) EPI_ROW((it) >> 2, (it) & 3)
; #define EPI_PACK8(v0, v1) (u32x4){pk2((v0)[0], (v0)[1]), pk2((v0)[2], (v0)[3]), pk2((v1)[0], (v1)[1]), pk2((v1)[2], (v1)[3])}
;     __device__ __forceinline__ void operator()(AccRef acc, const Unit& u, int wr, int wc, int fr, int fq) const {
;     ...
;         for (int it = 0; it < 8; ++it) { const int ai = it >> 2, m = it & 3, row = EPI_IT_ROW(it);
;             if (it + 1 < 8) {
; #pragma unroll
;                 for (int bj = 0; bj < 2; ++bj) { const size_t p = (size_t)EPI_IT_ROW(it + 1) * DM + EPI_COL(bj); xn[bj][0] = *(const f32x4*)(xin + p); xn[bj][1] = *(const f32x4*)(xin + p + 4); } }
;             float q = 0.f;
; #pragma unroll
;             for (int bj = 0; bj < 2; ++bj) { const size_t p = (size_t)row * DM + EPI_COL(bj);
;                 const f32x4 x0 = xc[bj][0] + acc[ai][bj][m][0], x1 = xc[bj][1] + acc[ai][bj][m][1];
;                 __builtin_nontemporal_store(x0, (f32x4*)(xout + p)); __builtin_nontemporal_store(x1, (f32x4*)(xout + p + 4));
;                 *(u32x4*)(xb + p) = EPI_PACK8(x0, x1);
;                 q += EPI_SQ8(x0, x1); }
;             q += __shfl_xor(q, 16); q += __shfl_xor(q, 32);
;             if (fq == 0) atomicAdd(ssout + row, q);
; #pragma unroll
;             for (int bj = 0; bj < 2; ++bj) { xc[bj][0] = xn[bj][0]; xc[bj][1] = xn[bj][1]; } }
.LBB0_805:
	s_or_b64 exec, exec, s[0:1]
	v_add_u32_e32 v80, 0xa0, v164
	v_ashrrev_i32_e32 v81, 31, v80
	s_waitcnt lgkmcnt(0)
	v_lshlrev_b64 v[48:49], 12, v[80:81]
	v_lshl_add_u64 v[48:49], s[48:49], 0, v[48:49]
	v_lshl_add_u64 v[84:85], v[162:163], 2, v[48:49]
	v_lshl_add_u64 v[82:83], v[160:161], 2, v[48:49]
	global_load_dwordx4 v[56:59], v[84:85], off offset:16 nt
	global_load_dwordx4 v[60:63], v[84:85], off nt
	global_load_dwordx4 v[48:51], v[82:83], off offset:16 nt
	global_load_dwordx4 v[52:55], v[82:83], off nt
	s_waitcnt vmcnt(12)
	v_pk_add_f32 v[46:47], v[46:47], v[78:79]
	v_pk_add_f32 v[44:45], v[44:45], v[76:77]
	v_pk_add_f32 v[42:43], v[42:43], v[74:75]
	v_pk_add_f32 v[40:41], v[40:41], v[72:73]
	global_store_dwordx4 v[100:101], v[44:47], off nt
	global_store_dwordx4 v[100:101], v[40:43], off offset:16 nt
	v_cvt_pk_bf16_f32 v72, v44, v45
	v_cvt_pk_bf16_f32 v74, v40, v41
	s_waitcnt vmcnt(12)
	v_pk_add_f32 v[38:39], v[38:39], v[70:71]
	v_mul_f32_e32 v45, v45, v45
	v_fmac_f32_e32 v45, v44, v44
	v_mul_f32_e32 v44, v47, v47
	v_fmac_f32_e32 v44, v46, v46
	v_mul_f32_e32 v41, v41, v41
	v_add_f32_e32 v44, v45, v44
	v_fmac_f32_e32 v41, v40, v40
	v_add_f32_e32 v40, v44, v41
	v_mul_f32_e32 v41, v43, v43
	v_fmac_f32_e32 v41, v42, v42
	v_pk_add_f32 v[36:37], v[36:37], v[68:69]
	v_cvt_pk_bf16_f32 v73, v46, v47
	v_add_f32_e32 v46, v41, v40
	v_pk_add_f32 v[40:41], v[32:33], v[64:65]
	v_mul_f32_e32 v32, v37, v37
	v_mul_f32_e32 v33, v39, v39
	v_fmac_f32_e32 v32, v36, v36
	v_fmac_f32_e32 v33, v38, v38
	v_add_f32_e32 v32, v32, v33
	v_mul_f32_e32 v33, v41, v41
	v_cvt_pk_bf16_f32 v75, v42, v43
	v_pk_add_f32 v[42:43], v[34:35], v[66:67]
	v_fmac_f32_e32 v33, v40, v40
	v_add_f32_e32 v32, v32, v33
	v_mul_f32_e32 v33, v43, v43
	v_fmac_f32_e32 v33, v42, v42
	v_add_f32_e32 v32, v33, v32
	v_add_f32_e32 v32, v46, v32
	ds_bpermute_b32 v33, v186, v32
	v_lshlrev_b64 v[86:87], 10, v[96:97]
	v_lshl_add_u64 v[88:89], v[86:87], 0, v[162:163]
	v_lshl_add_u64 v[76:77], v[88:89], 1, s[30:31]
	v_lshl_add_u64 v[44:45], v[86:87], 0, v[160:161]
	s_waitcnt lgkmcnt(0)
	v_add_f32_e32 v32, v32, v33
	ds_bpermute_b32 v33, v187, v32
	global_store_dwordx4 v[76:77], v[72:75], off
	global_store_dwordx4 v[98:99], v[36:39], off nt
	global_store_dwordx4 v[98:99], v[40:43], off offset:16 nt
	v_cvt_pk_bf16_f32 v35, v38, v39
	v_cvt_pk_bf16_f32 v34, v36, v37
	s_nop 0
	v_lshl_add_u64 v[38:39], v[44:45], 1, s[30:31]
	v_cvt_pk_bf16_f32 v36, v40, v41
	v_cvt_pk_bf16_f32 v37, v42, v43
	global_store_dwordx4 v[38:39], v[34:37], off
	s_and_saveexec_b64 s[0:1], vcc
	s_cbranch_execz .LBB0_807
	v_lshl_add_u64 v[34:35], v[96:97], 2, s[12:13]
	s_waitcnt lgkmcnt(0)
	v_add_f32_e32 v32, v32, v33
	global_atomic_add_f32 v[34:35], v32, off
.LBB0_807:
	s_or_b64 exec, exec, s[0:1]
	v_add_u32_e32 v64, 0xb0, v164
	v_ashrrev_i32_e32 v65, 31, v64
	s_waitcnt lgkmcnt(0)
	v_lshlrev_b64 v[32:33], 12, v[64:65]
	v_lshl_add_u64 v[32:33], s[48:49], 0, v[32:33]
	v_lshl_add_u64 v[68:69], v[162:163], 2, v[32:33]
	v_lshl_add_u64 v[66:67], v[160:161], 2, v[32:33]
	global_load_dwordx4 v[40:43], v[68:69], off offset:16 nt
	global_load_dwordx4 v[44:47], v[68:69], off nt
	global_load_dwordx4 v[32:35], v[66:67], off offset:16 nt
	global_load_dwordx4 v[36:39], v[66:67], off nt
	s_waitcnt vmcnt(12)
	v_pk_add_f32 v[30:31], v[30:31], v[62:63]
	v_pk_add_f32 v[28:29], v[28:29], v[60:61]
	v_pk_add_f32 v[26:27], v[26:27], v[58:59]
	v_pk_add_f32 v[24:25], v[24:25], v[56:57]
	global_store_dwordx4 v[84:85], v[28:31], off nt
	global_store_dwordx4 v[84:85], v[24:27], off offset:16 nt
	v_cvt_pk_bf16_f32 v56, v28, v29
	v_cvt_pk_bf16_f32 v58, v24, v25
	s_waitcnt vmcnt(12)
	v_pk_add_f32 v[22:23], v[22:23], v[54:55]
	v_mul_f32_e32 v29, v29, v29
	v_fmac_f32_e32 v29, v28, v28
	v_mul_f32_e32 v28, v31, v31
	v_fmac_f32_e32 v28, v30, v30
	v_mul_f32_e32 v25, v25, v25
	v_add_f32_e32 v28, v29, v28
	v_fmac_f32_e32 v25, v24, v24
	v_add_f32_e32 v24, v28, v25
	v_mul_f32_e32 v25, v27, v27
	v_fmac_f32_e32 v25, v26, v26
	v_pk_add_f32 v[20:21], v[20:21], v[52:53]
	v_cvt_pk_bf16_f32 v57, v30, v31
	v_add_f32_e32 v30, v25, v24
	v_pk_add_f32 v[24:25], v[16:17], v[48:49]
	v_mul_f32_e32 v16, v21, v21
	v_mul_f32_e32 v17, v23, v23
	v_fmac_f32_e32 v16, v20, v20
	v_fmac_f32_e32 v17, v22, v22
	v_add_f32_e32 v16, v16, v17
	v_mul_f32_e32 v17, v25, v25
	v_cvt_pk_bf16_f32 v59, v26, v27
	v_pk_add_f32 v[26:27], v[18:19], v[50:51]
	v_fmac_f32_e32 v17, v24, v24
	v_add_f32_e32 v16, v16, v17
	v_mul_f32_e32 v17, v27, v27
	v_fmac_f32_e32 v17, v26, v26
	v_add_f32_e32 v16, v17, v16
	v_add_f32_e32 v16, v30, v16
	ds_bpermute_b32 v17, v186, v16
	v_lshlrev_b64 v[70:71], 10, v[80:81]
	v_lshl_add_u64 v[72:73], v[70:71], 0, v[162:163]
	v_lshl_add_u64 v[60:61], v[72:73], 1, s[30:31]
	v_lshl_add_u64 v[28:29], v[70:71], 0, v[160:161]
	s_waitcnt lgkmcnt(0)
	v_add_f32_e32 v16, v16, v17
	ds_bpermute_b32 v17, v187, v16
	global_store_dwordx4 v[60:61], v[56:59], off
	global_store_dwordx4 v[82:83], v[20:23], off nt
	global_store_dwordx4 v[82:83], v[24:27], off offset:16 nt
	v_cvt_pk_bf16_f32 v19, v22, v23
	v_cvt_pk_bf16_f32 v18, v20, v21
	s_nop 0
	v_lshl_add_u64 v[22:23], v[28:29], 1, s[30:31]
	v_cvt_pk_bf16_f32 v20, v24, v25
	v_cvt_pk_bf16_f32 v21, v26, v27
	global_store_dwordx4 v[22:23], v[18:21], off
	s_and_saveexec_b64 s[0:1], vcc
	s_cbranch_execz .LBB0_809
	v_lshl_add_u64 v[18:19], v[80:81], 2, s[12:13]
	s_waitcnt lgkmcnt(0)
	v_add_f32_e32 v16, v16, v17
	global_atomic_add_f32 v[18:19], v16, off

; #define EPI_IT_ROW(it) EPI_ROW((it) >> 2, (it) & 3)
; #define EPI_PACK8(v0, v1) (u32x4){pk2((v0)[0], (v0)[1]), pk2((v0)[2], (v0)[3]), pk2((v1)[0], (v1)[1]), pk2((v1)[2], (v1)[3])}
;     __device__ __forceinline__ void operator()(AccRef acc, const Unit& u, int wr, int wc, int fr, int fq) const {
;     ...
;         for (int bj = 0; bj < 2; ++bj) { const size_t p = (size_t)EPI_IT_ROW(0) * DM + EPI_COL(bj); xc[bj][0] = *(const f32x4*)(xin + p); xc[bj][1] = *(const f32x4*)(xin + p + 4); }
; #pragma unroll
;         for (int it = 0; it < 8; ++it) { const int ai = it >> 2, m = it & 3, row = EPI_IT_ROW(it);
;             if (it + 1 < 8) {
; #pragma unroll
;                 for (int bj = 0; bj < 2; ++bj) { const size_t p = (size_t)EPI_IT_ROW(it + 1) * DM + EPI_COL(bj); xn[bj][0] = *(const f32x4*)(xin + p); xn[bj][1] = *(const f32x4*)(xin + p + 4); } }
;             float q = 0.f;
; #pragma unroll
;             for (int bj = 0; bj < 2; ++bj) { const size_t p = (size_t)row * DM + EPI_COL(bj);
;                 const f32x4 x0 = xc[bj][0] + acc[ai][bj][m][0], x1 = xc[bj][1] + acc[ai][bj][m][1];
;                 __builtin_nontemporal_store(x0, (f32x4*)(xout + p)); __builtin_nontemporal_store(x1, (f32x4*)(xout + p + 4));
;                 *(u32x4*)(xb + p) = EPI_PACK8(x0, x1);
;                 q += EPI_SQ8(x0, x1); }
;             q += __shfl_xor(q, 16); q += __shfl_xor(q, 32);
;             if (fq == 0) atomicAdd(ssout + row, q);
; #pragma unroll
;             for (int bj = 0; bj < 2; ++bj) { xc[bj][0] = xn[bj][0]; xc[bj][1] = xn[bj][1]; } }
.LBB0_1317:
	s_lshl_b32 s1, s34, 8
	v_mov_b32_e32 v128, v180
	v_mov_b32_e32 v186, v177
	s_add_i32 s1, s1, s59
	s_lshl_b32 s0, s0, 8
	s_or_b32 s0, s0, s60
	v_add_u32_e32 v164, s1, v128
	v_ashrrev_i32_e32 v165, 31, v164
	v_lshl_add_u32 v162, v186, 3, s0
	v_lshlrev_b64 v[128:129], 12, v[164:165]
	v_ashrrev_i32_e32 v163, 31, v162
	v_add_u32_e32 v160, 0x80, v162
	v_lshl_add_u64 v[128:129], s[48:49], 0, v[128:129]
	v_lshlrev_b64 v[130:131], 2, v[162:163]
	v_ashrrev_i32_e32 v161, 31, v160
	v_lshl_add_u64 v[178:179], v[128:129], 0, v[130:131]
	v_lshlrev_b64 v[132:133], 2, v[160:161]
	global_load_dwordx4 v[170:173], v[178:179], off offset:16 nt
	global_load_dwordx4 v[188:191], v[178:179], off nt
	v_lshl_add_u64 v[200:201], v[128:129], 0, v[132:133]
	global_load_dwordx4 v[192:195], v[200:201], off nt
	global_load_dwordx4 v[196:199], v[200:201], off offset:16 nt
	v_add_u32_e32 v166, 16, v164
	v_ashrrev_i32_e32 v167, 31, v166
	v_lshlrev_b64 v[128:129], 12, v[166:167]
	v_lshl_add_u64 v[128:129], s[48:49], 0, v[128:129]
	v_lshl_add_u64 v[174:175], v[128:129], 0, v[130:131]
	v_lshl_add_u64 v[168:169], v[128:129], 0, v[132:133]
	global_load_dwordx4 v[136:139], v[174:175], off offset:16 nt
	global_load_dwordx4 v[140:143], v[174:175], off nt
	global_load_dwordx4 v[128:131], v[168:169], off offset:16 nt
	global_load_dwordx4 v[132:135], v[168:169], off nt
	v_and_b32_e32 v202, 64, v185
	v_xor_b32_e32 v187, 16, v185
	v_add_u32_e32 v202, 64, v202
	v_cmp_lt_i32_e64 s[0:1], v187, v202
	v_cmp_eq_u32_e32 vcc, 0, v186
	v_xor_b32_e32 v203, 32, v185
	v_cndmask_b32_e64 v186, v185, v187, s[0:1]
	v_lshlrev_b32_e32 v186, 2, v186
	v_cmp_lt_i32_e64 s[0:1], v203, v202
	s_waitcnt vmcnt(0)
	v_pk_add_f32 v[122:123], v[122:123], v[172:173]
	v_pk_add_f32 v[126:127], v[126:127], v[190:191]
	v_pk_add_f32 v[124:125], v[124:125], v[188:189]
	v_pk_add_f32 v[118:119], v[118:119], v[194:195]
	v_pk_add_f32 v[116:117], v[116:117], v[192:193]
	v_pk_add_f32 v[120:121], v[120:121], v[170:171]
	v_pk_add_f32 v[170:171], v[112:113], v[196:197]
	global_store_dwordx4 v[178:179], v[124:127], off nt
	global_store_dwordx4 v[178:179], v[120:123], off offset:16 nt
	v_cvt_pk_bf16_f32 v112, v124, v125
	v_cvt_pk_bf16_f32 v113, v126, v127
	v_mul_f32_e32 v178, v117, v117
	v_mul_f32_e32 v125, v125, v125
	v_mul_f32_e32 v127, v127, v127
	v_mul_f32_e32 v179, v119, v119
	v_pk_add_f32 v[172:173], v[114:115], v[198:199]
	v_cvt_pk_bf16_f32 v114, v120, v121
	v_cvt_pk_bf16_f32 v115, v122, v123
	v_mul_f32_e32 v121, v121, v121
	v_mul_f32_e32 v123, v123, v123
	v_mul_f32_e32 v189, v171, v171
	v_fmac_f32_e32 v125, v124, v124
	v_fmac_f32_e32 v127, v126, v126
	v_fmac_f32_e32 v178, v116, v116
	v_fmac_f32_e32 v179, v118, v118
	v_mul_f32_e32 v190, v173, v173
	v_fmac_f32_e32 v121, v120, v120
	v_fmac_f32_e32 v123, v122, v122
	v_fmac_f32_e32 v189, v170, v170
	v_add_f32_e32 v120, v125, v127
	v_add_f32_e32 v122, v178, v179
	v_fmac_f32_e32 v190, v172, v172
	v_add_f32_e32 v120, v120, v121
	v_add_f32_e32 v121, v122, v189
	v_add_f32_e32 v120, v123, v120
	v_add_f32_e32 v121, v190, v121
	v_add_f32_e32 v120, v120, v121
	ds_bpermute_b32 v121, v186, v120
	v_cndmask_b32_e64 v187, v185, v203, s[0:1]
	v_lshlrev_b64 v[202:203], 10, v[164:165]
	v_lshl_add_u64 v[204:205], v[202:203], 0, v[162:163]
	v_lshl_add_u64 v[204:205], v[204:205], 1, s[24:25]
	global_store_dwordx4 v[204:205], v[112:115], off
	global_store_dwordx4 v[200:201], v[116:119], off nt
	global_store_dwordx4 v[200:201], v[170:173], off offset:16 nt
	s_waitcnt lgkmcnt(0)
	v_add_f32_e32 v112, v120, v121
	v_lshlrev_b32_e32 v187, 2, v187
	ds_bpermute_b32 v113, v187, v112
	v_lshl_add_u64 v[202:203], v[202:203], 0, v[160:161]
	v_lshl_add_u64 v[114:115], v[202:203], 1, s[24:25]
	v_cvt_pk_bf16_f32 v188, v116, v117
	v_cvt_pk_bf16_f32 v189, v118, v119
	v_cvt_pk_bf16_f32 v190, v170, v171
	v_cvt_pk_bf16_f32 v191, v172, v173
	global_store_dwordx4 v[114:115], v[188:191], off
	s_and_saveexec_b64 s[0:1], vcc
	v_readlane_b32 s72, v254, 6
	v_readlane_b32 s73, v254, 7
	v_readlane_b32 s74, v254, 8
	v_readlane_b32 s75, v254, 9
	s_cbranch_execz .LBB0_1319
	v_lshl_add_u64 v[114:115], v[164:165], 2, s[10:11]
	s_waitcnt lgkmcnt(0)
	v_add_f32_e32 v112, v112, v113
	global_atomic_add_f32 v[114:115], v112, off
.LBB0_1319:
	s_or_b64 exec, exec, s[0:1]
	v_add_u32_e32 v170, 32, v164
	v_ashrrev_i32_e32 v171, 31, v170
	s_waitcnt lgkmcnt(0)
	v_lshlrev_b64 v[112:113], 12, v[170:171]
	v_lshl_add_u64 v[112:113], s[48:49], 0, v[112:113]
	v_lshl_add_u64 v[178:179], v[162:163], 2, v[112:113]
	v_lshl_add_u64 v[172:173], v[160:161], 2, v[112:113]
	global_load_dwordx4 v[120:123], v[178:179], off offset:16 nt
	global_load_dwordx4 v[124:127], v[178:179], off nt
	global_load_dwordx4 v[112:115], v[172:173], off offset:16 nt
	global_load_dwordx4 v[116:119], v[172:173], off nt
	v_pk_add_f32 v[110:111], v[110:111], v[142:143]
	v_pk_add_f32 v[108:109], v[108:109], v[140:141]
	v_pk_add_f32 v[106:107], v[106:107], v[138:139]
	v_pk_add_f32 v[104:105], v[104:105], v[136:137]
	global_store_dwordx4 v[174:175], v[108:111], off nt
	global_store_dwordx4 v[174:175], v[104:107], off offset:16 nt
	v_cvt_pk_bf16_f32 v136, v108, v109
	v_cvt_pk_bf16_f32 v138, v104, v105
	v_pk_add_f32 v[102:103], v[102:103], v[134:135]
	v_mul_f32_e32 v109, v109, v109
	v_fmac_f32_e32 v109, v108, v108
	v_mul_f32_e32 v108, v111, v111
	v_fmac_f32_e32 v108, v110, v110
	v_mul_f32_e32 v105, v105, v105
	v_add_f32_e32 v108, v109, v108
	v_fmac_f32_e32 v105, v104, v104
	v_add_f32_e32 v104, v108, v105
	v_mul_f32_e32 v105, v107, v107
	v_fmac_f32_e32 v105, v106, v106
	v_pk_add_f32 v[100:101], v[100:101], v[132:133]
	v_cvt_pk_bf16_f32 v137, v110, v111
	v_add_f32_e32 v110, v105, v104
	v_pk_add_f32 v[104:105], v[96:97], v[128:129]
	v_mul_f32_e32 v96, v101, v101
	v_mul_f32_e32 v97, v103, v103
	v_fmac_f32_e32 v96, v100, v100
	v_fmac_f32_e32 v97, v102, v102
	v_add_f32_e32 v96, v96, v97
	v_mul_f32_e32 v97, v105, v105
	v_cvt_pk_bf16_f32 v139, v106, v107
	v_pk_add_f32 v[106:107], v[98:99], v[130:131]
	v_fmac_f32_e32 v97, v104, v104
	v_add_f32_e32 v96, v96, v97
	v_mul_f32_e32 v97, v107, v107
	v_fmac_f32_e32 v97, v106, v106
	v_add_f32_e32 v96, v97, v96
	v_add_f32_e32 v96, v110, v96
	ds_bpermute_b32 v97, v186, v96
	v_lshlrev_b64 v[188:189], 10, v[166:167]
	v_lshl_add_u64 v[190:191], v[188:189], 0, v[162:163]
	v_lshl_add_u64 v[140:141], v[190:191], 1, s[24:25]
	v_lshl_add_u64 v[108:109], v[188:189], 0, v[160:161]
	s_waitcnt lgkmcnt(0)
	v_add_f32_e32 v96, v96, v97
	ds_bpermute_b32 v97, v187, v96
	global_store_dwordx4 v[140:141], v[136:139], off
	global_store_dwordx4 v[168:169], v[100:103], off nt
	global_store_dwordx4 v[168:169], v[104:107], off offset:16 nt
	v_cvt_pk_bf16_f32 v99, v102, v103
	v_cvt_pk_bf16_f32 v98, v100, v101
	s_nop 0
	v_lshl_add_u64 v[102:103], v[108:109], 1, s[24:25]
	v_cvt_pk_bf16_f32 v100, v104, v105
	v_cvt_pk_bf16_f32 v101, v106, v107
	global_store_dwordx4 v[102:103], v[98:101], off
	s_and_saveexec_b64 s[0:1], vcc
	s_cbranch_execz .LBB0_1321
; #define EPI_IT_ROW(it) EPI_ROW((it) >> 2, (it) & 3)
; #define EPI_PACK8(v0, v1) (u32x4){pk2((v0)[0], (v0)[1]), pk2((v0)[2], (v0)[3]), pk2((v1)[0], (v1)[1]), pk2((v1)[2], (v1)[3])}
;     __device__ __forceinline__ void operator()(AccRef acc, const Unit& u, int wr, int wc, int fr, int fq) const {
;     ...
;         for (int it = 0; it < 8; ++it) { const int ai = it >> 2, m = it & 3, row = EPI_IT_ROW(it);
;             if (it + 1 < 8) {
; #pragma unroll
;                 for (int bj = 0; bj < 2; ++bj) { const size_t p = (size_t)EPI_IT_ROW(it + 1) * DM + EPI_COL(bj); xn[bj][0] = *(const f32x4*)(xin + p); xn[bj][1] = *(const f32x4*)(xin + p + 4); } }
;             float q = 0.f;
; #pragma unroll
;             for (int bj = 0; bj < 2; ++bj) { const size_t p = (size_t)row * DM + EPI_COL(bj);
;                 const f32x4 x0 = xc[bj][0] + acc[ai][bj][m][0], x1 = xc[bj][1] + acc[ai][bj][m][1];
;                 __builtin_nontemporal_store(x0, (f32x4*)(xout + p)); __builtin_nontemporal_store(x1, (f32x4*)(xout + p + 4));
;                 *(u32x4*)(xb + p) = EPI_PACK8(x0, x1);
;                 q += EPI_SQ8(x0, x1); }
;             q += __shfl_xor(q, 16); q += __shfl_xor(q, 32);
;             if (fq == 0) atomicAdd(ssout + row, q);
; #pragma unroll
;             for (int bj = 0; bj < 2; ++bj) { xc[bj][0] = xn[bj][0]; xc[bj][1] = xn[bj][1]; } }
	v_lshl_add_u64 v[98:99], v[166:167], 2, s[10:11]
	s_waitcnt lgkmcnt(0)
	v_add_f32_e32 v96, v96, v97
	global_atomic_add_f32 v[98:99], v96, off
.LBB0_1321:
	s_or_b64 exec, exec, s[0:1]
	v_add_u32_e32 v128, 48, v164
	v_ashrrev_i32_e32 v129, 31, v128
	s_waitcnt lgkmcnt(0)
	v_lshlrev_b64 v[96:97], 12, v[128:129]
	v_lshl_add_u64 v[96:97], s[48:49], 0, v[96:97]
	v_lshl_add_u64 v[132:133], v[162:163], 2, v[96:97]
	v_lshl_add_u64 v[130:131], v[160:161], 2, v[96:97]
	global_load_dwordx4 v[104:107], v[132:133], off offset:16 nt
	global_load_dwordx4 v[108:111], v[132:133], off nt
	global_load_dwordx4 v[96:99], v[130:131], off offset:16 nt
	global_load_dwordx4 v[100:103], v[130:131], off nt
	s_waitcnt vmcnt(12)
	v_pk_add_f32 v[94:95], v[94:95], v[126:127]
	v_pk_add_f32 v[92:93], v[92:93], v[124:125]
	v_pk_add_f32 v[90:91], v[90:91], v[122:123]
	v_pk_add_f32 v[88:89], v[88:89], v[120:121]
	global_store_dwordx4 v[178:179], v[92:95], off nt
	global_store_dwordx4 v[178:179], v[88:91], off offset:16 nt
	v_cvt_pk_bf16_f32 v120, v92, v93
	v_cvt_pk_bf16_f32 v122, v88, v89
	s_waitcnt vmcnt(12)
	v_pk_add_f32 v[86:87], v[86:87], v[118:119]
	v_mul_f32_e32 v93, v93, v93
	v_fmac_f32_e32 v93, v92, v92
	v_mul_f32_e32 v92, v95, v95
	v_fmac_f32_e32 v92, v94, v94
	v_mul_f32_e32 v89, v89, v89
	v_add_f32_e32 v92, v93, v92
	v_fmac_f32_e32 v89, v88, v88
	v_add_f32_e32 v88, v92, v89
	v_mul_f32_e32 v89, v91, v91
	v_fmac_f32_e32 v89, v90, v90
	v_pk_add_f32 v[84:85], v[84:85], v[116:117]
	v_cvt_pk_bf16_f32 v121, v94, v95
	v_add_f32_e32 v94, v89, v88
	v_pk_add_f32 v[88:89], v[80:81], v[112:113]
	v_mul_f32_e32 v80, v85, v85
	v_mul_f32_e32 v81, v87, v87
	v_fmac_f32_e32 v80, v84, v84
	v_fmac_f32_e32 v81, v86, v86
	v_add_f32_e32 v80, v80, v81
	v_mul_f32_e32 v81, v89, v89
	v_cvt_pk_bf16_f32 v123, v90, v91
	v_pk_add_f32 v[90:91], v[82:83], v[114:115]
	v_fmac_f32_e32 v81, v88, v88
	v_add_f32_e32 v80, v80, v81
	v_mul_f32_e32 v81, v91, v91
	v_fmac_f32_e32 v81, v90, v90
	v_add_f32_e32 v80, v81, v80
	v_add_f32_e32 v80, v94, v80
	ds_bpermute_b32 v81, v186, v80
	v_lshlrev_b64 v[134:135], 10, v[170:171]
	v_lshl_add_u64 v[136:137], v[134:135], 0, v[162:163]
	v_lshl_add_u64 v[124:125], v[136:137], 1, s[24:25]
	v_lshl_add_u64 v[92:93], v[134:135], 0, v[160:161]
	s_waitcnt lgkmcnt(0)
	v_add_f32_e32 v80, v80, v81
	ds_bpermute_b32 v81, v187, v80
	global_store_dwordx4 v[124:125], v[120:123], off
	global_store_dwordx4 v[172:173], v[84:87], off nt
	global_store_dwordx4 v[172:173], v[88:91], off offset:16 nt
	v_cvt_pk_bf16_f32 v83, v86, v87
	v_cvt_pk_bf16_f32 v82, v84, v85
	s_nop 0
	v_lshl_add_u64 v[86:87], v[92:93], 1, s[24:25]
	v_cvt_pk_bf16_f32 v84, v88, v89
	v_cvt_pk_bf16_f32 v85, v90, v91
	global_store_dwordx4 v[86:87], v[82:85], off
	s_and_saveexec_b64 s[0:1], vcc
	s_cbranch_execz .LBB0_1323
	v_lshl_add_u64 v[82:83], v[170:171], 2, s[10:11]
	s_waitcnt lgkmcnt(0)
	v_add_f32_e32 v80, v80, v81
	global_atomic_add_f32 v[82:83], v80, off
.LBB0_1323:
	s_or_b64 exec, exec, s[0:1]
	v_add_u32_e32 v112, 0x80, v164
	v_ashrrev_i32_e32 v113, 31, v112
	s_waitcnt lgkmcnt(0)
	v_lshlrev_b64 v[80:81], 12, v[112:113]
	v_lshl_add_u64 v[80:81], s[48:49], 0, v[80:81]
	v_lshl_add_u64 v[116:117], v[162:163], 2, v[80:81]
	v_lshl_add_u64 v[114:115], v[160:161], 2, v[80:81]
	global_load_dwordx4 v[88:91], v[116:117], off offset:16 nt
	global_load_dwordx4 v[92:95], v[116:117], off nt
	global_load_dwordx4 v[80:83], v[114:115], off offset:16 nt
	global_load_dwordx4 v[84:87], v[114:115], off nt
	s_waitcnt vmcnt(12)
	v_pk_add_f32 v[78:79], v[78:79], v[110:111]
	v_pk_add_f32 v[76:77], v[76:77], v[108:109]
	v_pk_add_f32 v[74:75], v[74:75], v[106:107]
	v_pk_add_f32 v[72:73], v[72:73], v[104:105]
	global_store_dwordx4 v[132:133], v[76:79], off nt
	global_store_dwordx4 v[132:133], v[72:75], off offset:16 nt
	v_cvt_pk_bf16_f32 v104, v76, v77
	v_cvt_pk_bf16_f32 v106, v72, v73
	s_waitcnt vmcnt(12)
	v_pk_add_f32 v[70:71], v[70:71], v[102:103]
	v_mul_f32_e32 v77, v77, v77
	v_fmac_f32_e32 v77, v76, v76
	v_mul_f32_e32 v76, v79, v79
	v_fmac_f32_e32 v76, v78, v78
	v_mul_f32_e32 v73, v73, v73
	v_add_f32_e32 v76, v77, v76
	v_fmac_f32_e32 v73, v72, v72
	v_add_f32_e32 v72, v76, v73
	v_mul_f32_e32 v73, v75, v75
	v_fmac_f32_e32 v73, v74, v74
	v_pk_add_f32 v[68:69], v[68:69], v[100:101]
	v_cvt_pk_bf16_f32 v105, v78, v79
	v_add_f32_e32 v78, v73, v72
	v_pk_add_f32 v[72:73], v[64:65], v[96:97]
	v_mul_f32_e32 v64, v69, v69
	v_mul_f32_e32 v65, v71, v71
	v_fmac_f32_e32 v64, v68, v68
	v_fmac_f32_e32 v65, v70, v70
	v_add_f32_e32 v64, v64, v65
	v_mul_f32_e32 v65, v73, v73
	v_cvt_pk_bf16_f32 v107, v74, v75
	v_pk_add_f32 v[74:75], v[66:67], v[98:99]
	v_fmac_f32_e32 v65, v72, v72
	v_add_f32_e32 v64, v64, v65
	v_mul_f32_e32 v65, v75, v75
	v_fmac_f32_e32 v65, v74, v74
	v_add_f32_e32 v64, v65, v64
	v_add_f32_e32 v64, v78, v64
	ds_bpermute_b32 v65, v186, v64
	v_lshlrev_b64 v[118:119], 10, v[128:129]
	v_lshl_add_u64 v[120:121], v[118:119], 0, v[162:163]
	v_lshl_add_u64 v[108:109], v[120:121], 1, s[24:25]
	v_lshl_add_u64 v[76:77], v[118:119], 0, v[160:161]
	s_waitcnt lgkmcnt(0)
	v_add_f32_e32 v64, v64, v65
	ds_bpermute_b32 v65, v187, v64
	global_store_dwordx4 v[108:109], v[104:107], off
	global_store_dwordx4 v[130:131], v[68:71], off nt
	global_store_dwordx4 v[130:131], v[72:75], off offset:16 nt
	v_cvt_pk_bf16_f32 v67, v70, v71
	v_cvt_pk_bf16_f32 v66, v68, v69
	s_nop 0
	v_lshl_add_u64 v[70:71], v[76:77], 1, s[24:25]
	v_cvt_pk_bf16_f32 v68, v72, v73
	v_cvt_pk_bf16_f32 v69, v74, v75
	global_store_dwordx4 v[70:71], v[66:69], off
	s_and_saveexec_b64 s[0:1], vcc
	s_cbranch_execz .LBB0_1325
	v_lshl_add_u64 v[66:67], v[128:129], 2, s[10:11]
	s_waitcnt lgkmcnt(0)
	v_add_f32_e32 v64, v64, v65
	global_atomic_add_f32 v[66:67], v64, off
; #define EPI_IT_ROW(it) EPI_ROW((it) >> 2, (it) & 3)
; #define EPI_PACK8(v0, v1) (u32x4){pk2((v0)[0], (v0)[1]), pk2((v0)[2], (v0)[3]), pk2((v1)[0], (v1)[1]), pk2((v1)[2], (v1)[3])}
;     __device__ __forceinline__ void operator()(AccRef acc, const Unit& u, int wr, int wc, int fr, int fq) const {
;     ...
;         for (int it = 0; it < 8; ++it) { const int ai = it >> 2, m = it & 3, row = EPI_IT_ROW(it);
;             if (it + 1 < 8) {
; #pragma unroll
;                 for (int bj = 0; bj < 2; ++bj) { const size_t p = (size_t)EPI_IT_ROW(it + 1) * DM + EPI_COL(bj); xn[bj][0] = *(const f32x4*)(xin + p); xn[bj][1] = *(const f32x4*)(xin + p + 4); } }
;             float q = 0.f;
; #pragma unroll
;             for (int bj = 0; bj < 2; ++bj) { const size_t p = (size_t)row * DM + EPI_COL(bj);
;                 const f32x4 x0 = xc[bj][0] + acc[ai][bj][m][0], x1 = xc[bj][1] + acc[ai][bj][m][1];
;                 __builtin_nontemporal_store(x0, (f32x4*)(xout + p)); __builtin_nontemporal_store(x1, (f32x4*)(xout + p + 4));
;                 *(u32x4*)(xb + p) = EPI_PACK8(x0, x1);
;                 q += EPI_SQ8(x0, x1); }
;             q += __shfl_xor(q, 16); q += __shfl_xor(q, 32);
;             if (fq == 0) atomicAdd(ssout + row, q);
; #pragma unroll
;             for (int bj = 0; bj < 2; ++bj) { xc[bj][0] = xn[bj][0]; xc[bj][1] = xn[bj][1]; } }
.LBB0_1325:
	s_or_b64 exec, exec, s[0:1]
	v_add_u32_e32 v96, 0x90, v164
	v_ashrrev_i32_e32 v97, 31, v96
	s_waitcnt lgkmcnt(0)
	v_lshlrev_b64 v[64:65], 12, v[96:97]
	v_lshl_add_u64 v[64:65], s[48:49], 0, v[64:65]
	v_lshl_add_u64 v[100:101], v[162:163], 2, v[64:65]
	v_lshl_add_u64 v[98:99], v[160:161], 2, v[64:65]
	global_load_dwordx4 v[72:75], v[100:101], off offset:16 nt
	global_load_dwordx4 v[76:79], v[100:101], off nt
	global_load_dwordx4 v[64:67], v[98:99], off offset:16 nt
	global_load_dwordx4 v[68:71], v[98:99], off nt
	s_waitcnt vmcnt(12)
	v_pk_add_f32 v[62:63], v[62:63], v[94:95]
	v_pk_add_f32 v[60:61], v[60:61], v[92:93]
	v_pk_add_f32 v[58:59], v[58:59], v[90:91]
	v_pk_add_f32 v[56:57], v[56:57], v[88:89]
	global_store_dwordx4 v[116:117], v[60:63], off nt
	global_store_dwordx4 v[116:117], v[56:59], off offset:16 nt
	v_cvt_pk_bf16_f32 v88, v60, v61
	v_cvt_pk_bf16_f32 v90, v56, v57
	s_waitcnt vmcnt(12)
	v_pk_add_f32 v[54:55], v[54:55], v[86:87]
	v_mul_f32_e32 v61, v61, v61
	v_fmac_f32_e32 v61, v60, v60
	v_mul_f32_e32 v60, v63, v63
	v_fmac_f32_e32 v60, v62, v62
	v_mul_f32_e32 v57, v57, v57
	v_add_f32_e32 v60, v61, v60
	v_fmac_f32_e32 v57, v56, v56
	v_add_f32_e32 v56, v60, v57
	v_mul_f32_e32 v57, v59, v59
	v_fmac_f32_e32 v57, v58, v58
	v_pk_add_f32 v[52:53], v[52:53], v[84:85]
	v_cvt_pk_bf16_f32 v89, v62, v63
	v_add_f32_e32 v62, v57, v56
	v_pk_add_f32 v[56:57], v[48:49], v[80:81]
	v_mul_f32_e32 v48, v53, v53
	v_mul_f32_e32 v49, v55, v55
	v_fmac_f32_e32 v48, v52, v52
	v_fmac_f32_e32 v49, v54, v54
	v_add_f32_e32 v48, v48, v49
	v_mul_f32_e32 v49, v57, v57
	v_cvt_pk_bf16_f32 v91, v58, v59
	v_pk_add_f32 v[58:59], v[50:51], v[82:83]
	v_fmac_f32_e32 v49, v56, v56
	v_add_f32_e32 v48, v48, v49
	v_mul_f32_e32 v49, v59, v59
	v_fmac_f32_e32 v49, v58, v58
	v_add_f32_e32 v48, v49, v48
	v_add_f32_e32 v48, v62, v48
	ds_bpermute_b32 v49, v186, v48
	v_lshlrev_b64 v[102:103], 10, v[112:113]
	v_lshl_add_u64 v[104:105], v[102:103], 0, v[162:163]
	v_lshl_add_u64 v[92:93], v[104:105], 1, s[24:25]
	v_lshl_add_u64 v[60:61], v[102:103], 0, v[160:161]
	s_waitcnt lgkmcnt(0)
	v_add_f32_e32 v48, v48, v49
	ds_bpermute_b32 v49, v187, v48
	global_store_dwordx4 v[92:93], v[88:91], off
	global_store_dwordx4 v[114:115], v[52:55], off nt
	global_store_dwordx4 v[114:115], v[56:59], off offset:16 nt
	v_cvt_pk_bf16_f32 v51, v54, v55
	v_cvt_pk_bf16_f32 v50, v52, v53
	s_nop 0
	v_lshl_add_u64 v[54:55], v[60:61], 1, s[24:25]
	v_cvt_pk_bf16_f32 v52, v56, v57
	v_cvt_pk_bf16_f32 v53, v58, v59
	global_store_dwordx4 v[54:55], v[50:53], off
	s_and_saveexec_b64 s[0:1], vcc
	s_cbranch_execz .LBB0_1327
	v_lshl_add_u64 v[50:51], v[112:113], 2, s[10:11]
	s_waitcnt lgkmcnt(0)
	v_add_f32_e32 v48, v48, v49
	global_atomic_add_f32 v[50:51], v48, off
; #define EPI_IT_ROW(it) EPI_ROW((it) >> 2, (it) & 3)
; #define EPI_PACK8(v0, v1) (u32x4){pk2((v0)[0], (v0)[1]), pk2((v0)[2], (v0)[3]), pk2((v1)[0], (v1)[1]), pk2((v1)[2], (v1)[3])}
;     __device__ __forceinline__ void operator()(AccRef acc, const Unit& u, int wr, int wc, int fr, int fq) const {
;     ...
;         for (int it = 0; it < 8; ++it) { const int ai = it >> 2, m = it & 3, row = EPI_IT_ROW(it);
;             if (it + 1 < 8) {
; #pragma unroll
;                 for (int bj = 0; bj < 2; ++bj) { const size_t p = (size_t)EPI_IT_ROW(it + 1) * DM + EPI_COL(bj); xn[bj][0] = *(const f32x4*)(xin + p); xn[bj][1] = *(const f32x4*)(xin + p + 4); } }
;             float q = 0.f;
; #pragma unroll
;             for (int bj = 0; bj < 2; ++bj) { const size_t p = (size_t)row * DM + EPI_COL(bj);
;                 const f32x4 x0 = xc[bj][0] + acc[ai][bj][m][0], x1 = xc[bj][1] + acc[ai][bj][m][1];
;                 __builtin_nontemporal_store(x0, (f32x4*)(xout + p)); __builtin_nontemporal_store(x1, (f32x4*)(xout + p + 4));
;                 *(u32x4*)(xb + p) = EPI_PACK8(x0, x1);
;                 q += EPI_SQ8(x0, x1); }
;             q += __shfl_xor(q, 16); q += __shfl_xor(q, 32);
;             if (fq == 0) atomicAdd(ssout + row, q);
; #pragma unroll
;             for (int bj = 0; bj < 2; ++bj) { xc[bj][0] = xn[bj][0]; xc[bj][1] = xn[bj][1]; } }
.LBB0_1327:
	s_or_b64 exec, exec, s[0:1]
	v_add_u32_e32 v80, 0xa0, v164
	v_ashrrev_i32_e32 v81, 31, v80
	s_waitcnt lgkmcnt(0)
	v_lshlrev_b64 v[48:49], 12, v[80:81]
	v_lshl_add_u64 v[48:49], s[48:49], 0, v[48:49]
	v_lshl_add_u64 v[84:85], v[162:163], 2, v[48:49]
	v_lshl_add_u64 v[82:83], v[160:161], 2, v[48:49]
	global_load_dwordx4 v[56:59], v[84:85], off offset:16 nt
	global_load_dwordx4 v[60:63], v[84:85], off nt
	global_load_dwordx4 v[48:51], v[82:83], off offset:16 nt
	global_load_dwordx4 v[52:55], v[82:83], off nt
	s_waitcnt vmcnt(12)
	v_pk_add_f32 v[46:47], v[46:47], v[78:79]
	v_pk_add_f32 v[44:45], v[44:45], v[76:77]
	v_pk_add_f32 v[42:43], v[42:43], v[74:75]
	v_pk_add_f32 v[40:41], v[40:41], v[72:73]
	global_store_dwordx4 v[100:101], v[44:47], off nt
	global_store_dwordx4 v[100:101], v[40:43], off offset:16 nt
	v_cvt_pk_bf16_f32 v72, v44, v45
	v_cvt_pk_bf16_f32 v74, v40, v41
	s_waitcnt vmcnt(12)
	v_pk_add_f32 v[38:39], v[38:39], v[70:71]
	v_mul_f32_e32 v45, v45, v45
	v_fmac_f32_e32 v45, v44, v44
	v_mul_f32_e32 v44, v47, v47
	v_fmac_f32_e32 v44, v46, v46
	v_mul_f32_e32 v41, v41, v41
	v_add_f32_e32 v44, v45, v44
	v_fmac_f32_e32 v41, v40, v40
	v_add_f32_e32 v40, v44, v41
	v_mul_f32_e32 v41, v43, v43
	v_fmac_f32_e32 v41, v42, v42
	v_pk_add_f32 v[36:37], v[36:37], v[68:69]
	v_cvt_pk_bf16_f32 v73, v46, v47
	v_add_f32_e32 v46, v41, v40
	v_pk_add_f32 v[40:41], v[32:33], v[64:65]
	v_mul_f32_e32 v32, v37, v37
	v_mul_f32_e32 v33, v39, v39
	v_fmac_f32_e32 v32, v36, v36
	v_fmac_f32_e32 v33, v38, v38
	v_add_f32_e32 v32, v32, v33
	v_mul_f32_e32 v33, v41, v41
	v_cvt_pk_bf16_f32 v75, v42, v43
	v_pk_add_f32 v[42:43], v[34:35], v[66:67]
	v_fmac_f32_e32 v33, v40, v40
	v_add_f32_e32 v32, v32, v33
	v_mul_f32_e32 v33, v43, v43
	v_fmac_f32_e32 v33, v42, v42
	v_add_f32_e32 v32, v33, v32
	v_add_f32_e32 v32, v46, v32
	ds_bpermute_b32 v33, v186, v32
	v_lshlrev_b64 v[86:87], 10, v[96:97]
	v_lshl_add_u64 v[88:89], v[86:87], 0, v[162:163]
	v_lshl_add_u64 v[76:77], v[88:89], 1, s[24:25]
	v_lshl_add_u64 v[44:45], v[86:87], 0, v[160:161]
	s_waitcnt lgkmcnt(0)
	v_add_f32_e32 v32, v32, v33
	ds_bpermute_b32 v33, v187, v32
	global_store_dwordx4 v[76:77], v[72:75], off
	global_store_dwordx4 v[98:99], v[36:39], off nt
	global_store_dwordx4 v[98:99], v[40:43], off offset:16 nt
	v_cvt_pk_bf16_f32 v35, v38, v39
	v_cvt_pk_bf16_f32 v34, v36, v37
	s_nop 0
	v_lshl_add_u64 v[38:39], v[44:45], 1, s[24:25]
	v_cvt_pk_bf16_f32 v36, v40, v41
	v_cvt_pk_bf16_f32 v37, v42, v43
	global_store_dwordx4 v[38:39], v[34:37], off
	s_and_saveexec_b64 s[0:1], vcc
	s_cbranch_execz .LBB0_1329
	v_lshl_add_u64 v[34:35], v[96:97], 2, s[10:11]
	s_waitcnt lgkmcnt(0)
	v_add_f32_e32 v32, v32, v33
	global_atomic_add_f32 v[34:35], v32, off
.LBB0_1329:
	s_or_b64 exec, exec, s[0:1]
	v_add_u32_e32 v64, 0xb0, v164
	v_ashrrev_i32_e32 v65, 31, v64
	s_waitcnt lgkmcnt(0)
	v_lshlrev_b64 v[32:33], 12, v[64:65]
	v_lshl_add_u64 v[32:33], s[48:49], 0, v[32:33]
	v_lshl_add_u64 v[68:69], v[162:163], 2, v[32:33]
	v_lshl_add_u64 v[66:67], v[160:161], 2, v[32:33]
	global_load_dwordx4 v[40:43], v[68:69], off offset:16 nt
	global_load_dwordx4 v[44:47], v[68:69], off nt
	global_load_dwordx4 v[32:35], v[66:67], off offset:16 nt
	global_load_dwordx4 v[36:39], v[66:67], off nt
	s_waitcnt vmcnt(12)
	v_pk_add_f32 v[30:31], v[30:31], v[62:63]
	v_pk_add_f32 v[28:29], v[28:29], v[60:61]
	v_pk_add_f32 v[26:27], v[26:27], v[58:59]
	v_pk_add_f32 v[24:25], v[24:25], v[56:57]
	global_store_dwordx4 v[84:85], v[28:31], off nt
	global_store_dwordx4 v[84:85], v[24:27], off offset:16 nt
	v_cvt_pk_bf16_f32 v56, v28, v29
	v_cvt_pk_bf16_f32 v58, v24, v25
	s_waitcnt vmcnt(12)
	v_pk_add_f32 v[22:23], v[22:23], v[54:55]
	v_mul_f32_e32 v29, v29, v29
	v_fmac_f32_e32 v29, v28, v28
	v_mul_f32_e32 v28, v31, v31
	v_fmac_f32_e32 v28, v30, v30
	v_mul_f32_e32 v25, v25, v25
	v_add_f32_e32 v28, v29, v28
	v_fmac_f32_e32 v25, v24, v24
	v_add_f32_e32 v24, v28, v25
	v_mul_f32_e32 v25, v27, v27
	v_fmac_f32_e32 v25, v26, v26
	v_pk_add_f32 v[20:21], v[20:21], v[52:53]
	v_cvt_pk_bf16_f32 v57, v30, v31
	v_add_f32_e32 v30, v25, v24
	v_pk_add_f32 v[24:25], v[16:17], v[48:49]
	v_mul_f32_e32 v16, v21, v21
	v_mul_f32_e32 v17, v23, v23
	v_fmac_f32_e32 v16, v20, v20
	v_fmac_f32_e32 v17, v22, v22
	v_add_f32_e32 v16, v16, v17
	v_mul_f32_e32 v17, v25, v25
	v_cvt_pk_bf16_f32 v59, v26, v27
	v_pk_add_f32 v[26:27], v[18:19], v[50:51]
	v_fmac_f32_e32 v17, v24, v24
	v_add_f32_e32 v16, v16, v17
	v_mul_f32_e32 v17, v27, v27
	v_fmac_f32_e32 v17, v26, v26
	v_add_f32_e32 v16, v17, v16
	v_add_f32_e32 v16, v30, v16
	ds_bpermute_b32 v17, v186, v16
	v_lshlrev_b64 v[70:71], 10, v[80:81]
	v_lshl_add_u64 v[72:73], v[70:71], 0, v[162:163]
	v_lshl_add_u64 v[60:61], v[72:73], 1, s[24:25]
	v_lshl_add_u64 v[28:29], v[70:71], 0, v[160:161]
	s_waitcnt lgkmcnt(0)
	v_add_f32_e32 v16, v16, v17
	ds_bpermute_b32 v17, v187, v16
	global_store_dwordx4 v[60:61], v[56:59], off
	global_store_dwordx4 v[82:83], v[20:23], off nt
	global_store_dwordx4 v[82:83], v[24:27], off offset:16 nt
	v_cvt_pk_bf16_f32 v19, v22, v23
	v_cvt_pk_bf16_f32 v18, v20, v21
	s_nop 0
	v_lshl_add_u64 v[22:23], v[28:29], 1, s[24:25]
	v_cvt_pk_bf16_f32 v20, v24, v25
	v_cvt_pk_bf16_f32 v21, v26, v27
	global_store_dwordx4 v[22:23], v[18:21], off
	s_and_saveexec_b64 s[0:1], vcc
	s_cbranch_execz .LBB0_1331
	v_lshl_add_u64 v[18:19], v[80:81], 2, s[10:11]
	s_waitcnt lgkmcnt(0)
	v_add_f32_e32 v16, v16, v17
	global_atomic_add_f32 v[18:19], v16, off

; #define EPI_IT_ROW(it) EPI_ROW((it) >> 2, (it) & 3)
; #define EPI_PACK8(v0, v1) (u32x4){pk2((v0)[0], (v0)[1]), pk2((v0)[2], (v0)[3]), pk2((v1)[0], (v1)[1]), pk2((v1)[2], (v1)[3])}
;     __device__ __forceinline__ void operator()(AccRef acc, const Unit& u, int wr, int wc, int fr, int fq) const {
;     ...
;         for (int bj = 0; bj < 2; ++bj) { const size_t p = (size_t)EPI_IT_ROW(0) * DM + EPI_COL(bj); xc[bj][0] = *(const f32x4*)(xin + p); xc[bj][1] = *(const f32x4*)(xin + p + 4); }
; #pragma unroll
;         for (int it = 0; it < 8; ++it) { const int ai = it >> 2, m = it & 3, row = EPI_IT_ROW(it);
;             if (it + 1 < 8) {
; #pragma unroll
;                 for (int bj = 0; bj < 2; ++bj) { const size_t p = (size_t)EPI_IT_ROW(it + 1) * DM + EPI_COL(bj); xn[bj][0] = *(const f32x4*)(xin + p); xn[bj][1] = *(const f32x4*)(xin + p + 4); } }
;             float q = 0.f;
; #pragma unroll
;             for (int bj = 0; bj < 2; ++bj) { const size_t p = (size_t)row * DM + EPI_COL(bj);
;                 const f32x4 x0 = xc[bj][0] + acc[ai][bj][m][0], x1 = xc[bj][1] + acc[ai][bj][m][1];
;                 __builtin_nontemporal_store(x0, (f32x4*)(xout + p)); __builtin_nontemporal_store(x1, (f32x4*)(xout + p + 4));
;                 *(u32x4*)(xb + p) = EPI_PACK8(x0, x1);
;                 q += EPI_SQ8(x0, x1); }
;             q += __shfl_xor(q, 16); q += __shfl_xor(q, 32);
;             if (fq == 0) atomicAdd(ssout + row, q);
; #pragma unroll
;             for (int bj = 0; bj < 2; ++bj) { xc[bj][0] = xn[bj][0]; xc[bj][1] = xn[bj][1]; } }
.LBB0_1652:
	s_lshl_b32 s0, s60, 8
	v_mov_b32_e32 v128, v180
	v_mov_b32_e32 v186, v177
	s_add_i32 s0, s0, s38
	v_and_b32_e32 v202, 64, v185
	v_add_u32_e32 v164, s0, v128
	s_lshl_b32 s0, s59, 8
	s_or_b32 s0, s0, s39
	v_ashrrev_i32_e32 v165, 31, v164
	v_lshl_add_u32 v162, v186, 3, s0
	v_lshlrev_b64 v[128:129], 12, v[164:165]
	v_ashrrev_i32_e32 v163, 31, v162
	v_add_u32_e32 v160, 0x80, v162
	v_lshl_add_u64 v[128:129], s[48:49], 0, v[128:129]
	v_lshlrev_b64 v[130:131], 2, v[162:163]
	v_ashrrev_i32_e32 v161, 31, v160
	v_lshl_add_u64 v[178:179], v[128:129], 0, v[130:131]
	v_lshlrev_b64 v[132:133], 2, v[160:161]
	global_load_dwordx4 v[170:173], v[178:179], off offset:16 nt
	global_load_dwordx4 v[188:191], v[178:179], off nt
	v_lshl_add_u64 v[200:201], v[128:129], 0, v[132:133]
	global_load_dwordx4 v[192:195], v[200:201], off nt
	global_load_dwordx4 v[196:199], v[200:201], off offset:16 nt
	v_add_u32_e32 v166, 16, v164
	v_ashrrev_i32_e32 v167, 31, v166
	v_lshlrev_b64 v[128:129], 12, v[166:167]
	v_lshl_add_u64 v[128:129], s[48:49], 0, v[128:129]
	v_lshl_add_u64 v[174:175], v[128:129], 0, v[130:131]
	v_lshl_add_u64 v[168:169], v[128:129], 0, v[132:133]
	global_load_dwordx4 v[136:139], v[174:175], off offset:16 nt
	global_load_dwordx4 v[140:143], v[174:175], off nt
	global_load_dwordx4 v[128:131], v[168:169], off offset:16 nt
	global_load_dwordx4 v[132:135], v[168:169], off nt
	v_xor_b32_e32 v187, 16, v185
	v_add_u32_e32 v202, 64, v202
	v_cmp_lt_i32_e64 s[0:1], v187, v202
	v_cmp_eq_u32_e32 vcc, 0, v186
	v_xor_b32_e32 v203, 32, v185
	v_cndmask_b32_e64 v186, v185, v187, s[0:1]
	v_lshlrev_b32_e32 v186, 2, v186
	v_cmp_lt_i32_e64 s[0:1], v203, v202
	s_waitcnt vmcnt(0)
	v_pk_add_f32 v[122:123], v[122:123], v[172:173]
	v_pk_add_f32 v[126:127], v[126:127], v[190:191]
	v_pk_add_f32 v[124:125], v[124:125], v[188:189]
	v_pk_add_f32 v[118:119], v[118:119], v[194:195]
	v_pk_add_f32 v[116:117], v[116:117], v[192:193]
	v_pk_add_f32 v[120:121], v[120:121], v[170:171]
	v_pk_add_f32 v[170:171], v[112:113], v[196:197]
	global_store_dwordx4 v[178:179], v[124:127], off nt
	global_store_dwordx4 v[178:179], v[120:123], off offset:16 nt
	v_cvt_pk_bf16_f32 v112, v124, v125
	v_cvt_pk_bf16_f32 v113, v126, v127
	v_mul_f32_e32 v178, v117, v117
	v_mul_f32_e32 v125, v125, v125
	v_mul_f32_e32 v127, v127, v127
	v_mul_f32_e32 v179, v119, v119
	v_pk_add_f32 v[172:173], v[114:115], v[198:199]
	v_cvt_pk_bf16_f32 v114, v120, v121
	v_cvt_pk_bf16_f32 v115, v122, v123
	v_mul_f32_e32 v121, v121, v121
	v_mul_f32_e32 v123, v123, v123
	v_mul_f32_e32 v189, v171, v171
	v_fmac_f32_e32 v125, v124, v124
	v_fmac_f32_e32 v127, v126, v126
	v_fmac_f32_e32 v178, v116, v116
	v_fmac_f32_e32 v179, v118, v118
	v_mul_f32_e32 v190, v173, v173
	v_fmac_f32_e32 v121, v120, v120
	v_fmac_f32_e32 v123, v122, v122
	v_fmac_f32_e32 v189, v170, v170
	v_add_f32_e32 v120, v125, v127
	v_add_f32_e32 v122, v178, v179
	v_fmac_f32_e32 v190, v172, v172
	v_add_f32_e32 v120, v120, v121
	v_add_f32_e32 v121, v122, v189
	v_add_f32_e32 v120, v123, v120
	v_add_f32_e32 v121, v190, v121
	v_add_f32_e32 v120, v120, v121
	ds_bpermute_b32 v121, v186, v120
	v_cndmask_b32_e64 v187, v185, v203, s[0:1]
	v_lshlrev_b64 v[202:203], 10, v[164:165]
	v_lshl_add_u64 v[204:205], v[202:203], 0, v[162:163]
	v_lshl_add_u64 v[204:205], v[204:205], 1, s[30:31]
	global_store_dwordx4 v[204:205], v[112:115], off
	global_store_dwordx4 v[200:201], v[116:119], off nt
	global_store_dwordx4 v[200:201], v[170:173], off offset:16 nt
	s_waitcnt lgkmcnt(0)
	v_add_f32_e32 v112, v120, v121
	v_lshlrev_b32_e32 v187, 2, v187
	ds_bpermute_b32 v113, v187, v112
	v_lshl_add_u64 v[202:203], v[202:203], 0, v[160:161]
	v_lshl_add_u64 v[114:115], v[202:203], 1, s[30:31]
	v_cvt_pk_bf16_f32 v188, v116, v117
	v_cvt_pk_bf16_f32 v189, v118, v119
	v_cvt_pk_bf16_f32 v190, v170, v171
	v_cvt_pk_bf16_f32 v191, v172, v173
	global_store_dwordx4 v[114:115], v[188:191], off
	s_and_saveexec_b64 s[0:1], vcc
	s_cbranch_execz .LBB0_1654
	v_lshl_add_u64 v[114:115], v[164:165], 2, s[12:13]
	s_waitcnt lgkmcnt(0)
	v_add_f32_e32 v112, v112, v113
	global_atomic_add_f32 v[114:115], v112, off
